# removed 16 redundant vmcnt(0) drains before ds_read in the four GEMM K-loops (counted vmcnt(8)+barrier covers)
# speedup vs baseline: 1.0419x; 1.0419x over previous
; #define STAGE(bufoff, GB) do { const char* g_ = (GB); \
;         _Pragma("unroll") for (int i_ = 0; i_ < 2; ++i_) __builtin_amdgcn_global_load_lds((const unsigned*)(g_ + voff[i_]), (LAS3 unsigned*)(L + (bufoff) + stoff + i_ * 8192), 16, 0, 0); } while (0)
; #define LDA(dst, b, h) do { _Pragma("unroll") for (int m = 0; m < 4; ++m) _Pragma("unroll") for (int k = 0; k < 2; ++k) dst[m][k] = *(const LAS3 bf16x8*)(L + SA(b, h) + aoff + m * 2048 + k * 1024); } while (0)
; #define LDB(dst, b, h) do { _Pragma("unroll") for (int n = 0; n < 2; ++n) _Pragma("unroll") for (int k = 0; k < 2; ++k) dst[n][k] = *(const LAS3 bf16x8*)(L + SB(b, h) + boff + n * 2048 + k * 1024); } while (0)
; #define WAIT_V(n) asm volatile("s_waitcnt vmcnt(" #n ")" ::: "memory")
; #define WAIT_L(n) asm volatile("s_waitcnt lgkmcnt(" #n ")" ::: "memory")
; #define BAR __builtin_amdgcn_s_barrier()
; #define SCHED __builtin_amdgcn_sched_barrier(0)
; template <int EPI>
; DI void gemm_phase(const bf16_t* __restrict__ A, const bf16_t* __restrict__ Bt, const int K, const int N, const Params& p, const int layer_j, char* lds) {
;     ...
;         for (int t = 0; t < nt; t += 2) {
;             const bool last = (t == nt - 2);
;             const char* a1 = cA + (size_t)(t + 1) * kstep;
;             const char* a2 = last ? nA : cA + (size_t)(t + 2) * kstep; const char* b2 = last ? nB : cB + (size_t)(t + 2) * kstep;
;             const char* a3 = a2 + kstep; const char* b3 = b2 + kstep;
;             LDB(B0, 0, 0); LDB(B1, 0, 1); SCHED; LDA(At, 0, 0); STAGE(SA(1, 1), a1 + hstep);
;             WAIT_V(8); WAIT_L(0); BAR; MMA(0, 0, At, B0); MMA(0, 1, At, B1); BAR; SCHED;
;             LDA(At, 0, 1); STAGE(SB(0, 0), b2); STAGE(SB(0, 1), b2 + hstep); STAGE(SA(0, 0), a2);
;             WAIT_V(8); WAIT_L(0); BAR; MMA(1, 0, At, B0); MMA(1, 1, At, B1); BAR; SCHED;
.LBB0_43:
	v_add_u32_e32 v164, 0x10000, v138
	v_add_u32_e32 v180, 0x14000, v138
	s_add_u32 s6, s38, s28
	ds_read_b128 v[152:155], v164
	ds_read_b128 v[156:159], v164 offset:1024
	ds_read_b128 v[160:163], v164 offset:2048
	ds_read_b128 v[164:167], v164 offset:3072
	ds_read_b128 v[168:171], v180
	ds_read_b128 v[172:175], v180 offset:1024
	ds_read_b128 v[176:179], v180 offset:2048
	ds_read_b128 v[180:183], v180 offset:3072
	s_addc_u32 s7, s39, s29
	s_add_u32 s6, s6, 0x6681100
	s_addc_u32 s7, s7, 0
	s_add_u32 s30, vcc_lo, s28
	s_addc_u32 s31, vcc_hi, s29
	s_cmpk_eq_i32 s28, 0x700
	s_cselect_b32 s35, s17, s7
	s_cselect_b32 s34, s13, s6
	s_cselect_b32 s31, s88, s31
	s_cselect_b32 s30, s25, s30
	v_add_u32_e32 v194, 0xc000, v136
	v_lshl_add_u64 v[192:193], v[134:135], 0, s[28:29]
	v_readfirstlane_b32 s6, v194
	v_add_u32_e32 v194, 0xe000, v136
	s_mov_b32 m0, s6
	v_readfirstlane_b32 s6, v194
	ds_read_b128 v[184:187], v137
	ds_read_b128 v[188:191], v137 offset:1024
	ds_read_b128 v[204:207], v137 offset:2048
	ds_read_b128 v[208:211], v137 offset:3072
	ds_read_b128 v[212:215], v137 offset:4096
	ds_read_b128 v[216:219], v137 offset:5120
	ds_read_b128 v[220:223], v137 offset:6144
	ds_read_b128 v[224:227], v137 offset:7168
	global_load_lds_dwordx4 v[192:193], off
	v_lshl_add_u64 v[192:193], v[132:133], 0, s[28:29]
	s_mov_b32 m0, s6
	s_nop 0
	global_load_lds_dwordx4 v[192:193], off
	s_waitcnt vmcnt(8)
	s_waitcnt lgkmcnt(0)
	s_barrier
	s_setprio 1
	s_waitcnt lgkmcnt(0)
	v_mfma_f32_16x16x32_bf16 v[126:129], v[152:155], v[184:187], v[126:129]
	v_mfma_f32_16x16x32_bf16 v[118:121], v[160:163], v[184:187], v[118:121]
	v_mfma_f32_16x16x32_bf16 v[110:113], v[152:155], v[204:207], v[110:113]
	v_mfma_f32_16x16x32_bf16 v[102:105], v[160:163], v[204:207], v[102:105]
	v_mfma_f32_16x16x32_bf16 v[94:97], v[152:155], v[212:215], v[94:97]
	v_mfma_f32_16x16x32_bf16 v[86:89], v[160:163], v[212:215], v[86:89]
	v_mfma_f32_16x16x32_bf16 v[78:81], v[152:155], v[220:223], v[78:81]
	v_mfma_f32_16x16x32_bf16 v[70:73], v[160:163], v[220:223], v[70:73]
	v_mfma_f32_16x16x32_bf16 v[126:129], v[156:159], v[188:191], v[126:129]
	v_mfma_f32_16x16x32_bf16 v[118:121], v[164:167], v[188:191], v[118:121]
	v_mfma_f32_16x16x32_bf16 v[110:113], v[156:159], v[208:211], v[110:113]
	v_mfma_f32_16x16x32_bf16 v[102:105], v[164:167], v[208:211], v[102:105]
	v_mfma_f32_16x16x32_bf16 v[94:97], v[156:159], v[216:219], v[94:97]
	v_mfma_f32_16x16x32_bf16 v[86:89], v[164:167], v[216:219], v[86:89]
	v_mfma_f32_16x16x32_bf16 v[78:81], v[156:159], v[224:227], v[78:81]
	v_mfma_f32_16x16x32_bf16 v[70:73], v[164:167], v[224:227], v[70:73]
	s_setprio 0
	s_setprio 1
	v_mfma_f32_16x16x32_bf16 v[122:125], v[168:171], v[184:187], v[122:125]
	v_mfma_f32_16x16x32_bf16 v[114:117], v[176:179], v[184:187], v[114:117]
	v_mfma_f32_16x16x32_bf16 v[106:109], v[168:171], v[204:207], v[106:109]
	v_mfma_f32_16x16x32_bf16 v[98:101], v[176:179], v[204:207], v[98:101]
	v_mfma_f32_16x16x32_bf16 v[90:93], v[168:171], v[212:215], v[90:93]
	v_mfma_f32_16x16x32_bf16 v[82:85], v[176:179], v[212:215], v[82:85]
	v_mfma_f32_16x16x32_bf16 v[74:77], v[168:171], v[220:223], v[74:77]
	v_mfma_f32_16x16x32_bf16 v[66:69], v[176:179], v[220:223], v[66:69]
	v_mfma_f32_16x16x32_bf16 v[122:125], v[172:175], v[188:191], v[122:125]
	v_mfma_f32_16x16x32_bf16 v[114:117], v[180:183], v[188:191], v[114:117]
	v_mfma_f32_16x16x32_bf16 v[106:109], v[172:175], v[208:211], v[106:109]
	v_mfma_f32_16x16x32_bf16 v[98:101], v[180:183], v[208:211], v[98:101]
	v_mfma_f32_16x16x32_bf16 v[90:93], v[172:175], v[216:219], v[90:93]
	v_mfma_f32_16x16x32_bf16 v[82:85], v[180:183], v[216:219], v[82:85]
	v_mfma_f32_16x16x32_bf16 v[74:77], v[172:175], v[224:227], v[74:77]
	v_mfma_f32_16x16x32_bf16 v[66:69], v[180:183], v[224:227], v[66:69]
	s_setprio 0
	s_barrier
	v_readfirstlane_b32 s6, v139
	v_lshl_add_u64 v[192:193], s[30:31], 0, v[32:33]
	s_mov_b32 m0, s6
	v_readfirstlane_b32 s6, v140
	ds_read_b128 v[184:187], v137 offset:16384
	ds_read_b128 v[188:191], v137 offset:17408
	ds_read_b128 v[204:207], v137 offset:18432
	ds_read_b128 v[208:211], v137 offset:19456
	ds_read_b128 v[212:215], v137 offset:20480
	ds_read_b128 v[216:219], v137 offset:21504
	ds_read_b128 v[220:223], v137 offset:22528
	ds_read_b128 v[224:227], v137 offset:23552
	global_load_lds_dwordx4 v[192:193], off
	s_mov_b32 m0, s6
	s_add_u32 s6, s30, 0x40000
	v_lshl_add_u64 v[194:195], s[30:31], 0, v[130:131]
	s_addc_u32 s7, s31, 0
	v_readfirstlane_b32 s10, v141
	global_load_lds_dwordx4 v[194:195], off
	v_lshl_add_u64 v[228:229], s[6:7], 0, v[32:33]
	s_mov_b32 m0, s10
	v_lshl_add_u64 v[230:231], s[34:35], 0, v[130:131]
	global_load_lds_dwordx4 v[228:229], off
	v_lshl_add_u64 v[228:229], s[6:7], 0, v[130:131]
	v_readfirstlane_b32 s6, v142
	s_mov_b32 m0, s6
	v_readfirstlane_b32 s6, v136
	global_load_lds_dwordx4 v[228:229], off
	v_lshl_add_u64 v[228:229], s[34:35], 0, v[32:33]
	s_mov_b32 m0, s6
	v_readfirstlane_b32 s6, v143
	global_load_lds_dwordx4 v[228:229], off
	s_mov_b32 m0, s6
	s_nop 0
	global_load_lds_dwordx4 v[230:231], off
	s_waitcnt vmcnt(8)
	s_waitcnt lgkmcnt(0)
	s_barrier
; #define STAGE(bufoff, GB) do { const char* g_ = (GB); \
;         _Pragma("unroll") for (int i_ = 0; i_ < 2; ++i_) __builtin_amdgcn_global_load_lds((const unsigned*)(g_ + voff[i_]), (LAS3 unsigned*)(L + (bufoff) + stoff + i_ * 8192), 16, 0, 0); } while (0)
; #define LDA(dst, b, h) do { _Pragma("unroll") for (int m = 0; m < 4; ++m) _Pragma("unroll") for (int k = 0; k < 2; ++k) dst[m][k] = *(const LAS3 bf16x8*)(L + SA(b, h) + aoff + m * 2048 + k * 1024); } while (0)
; #define LDB(dst, b, h) do { _Pragma("unroll") for (int n = 0; n < 2; ++n) _Pragma("unroll") for (int k = 0; k < 2; ++k) dst[n][k] = *(const LAS3 bf16x8*)(L + SB(b, h) + boff + n * 2048 + k * 1024); } while (0)
; #define WAIT_V(n) asm volatile("s_waitcnt vmcnt(" #n ")" ::: "memory")
; #define WAIT_L(n) asm volatile("s_waitcnt lgkmcnt(" #n ")" ::: "memory")
; #define BAR __builtin_amdgcn_s_barrier()
; #define SCHED __builtin_amdgcn_sched_barrier(0)
; template <int EPI>
; DI void gemm_phase(const bf16_t* __restrict__ A, const bf16_t* __restrict__ Bt, const int K, const int N, const Params& p, const int layer_j, char* lds) {
;     ...
;             WAIT_V(8); WAIT_L(0); BAR; MMA(1, 0, At, B0); MMA(1, 1, At, B1); BAR; SCHED;
;             LDB(B0, 1, 0); LDB(B1, 1, 1); SCHED; LDA(At, 1, 0); STAGE(SA(0, 1), a2 + hstep);
;             WAIT_V(8); WAIT_L(0); BAR; MMA(0, 0, At, B0); MMA(0, 1, At, B1); BAR; SCHED;
	s_setprio 1
	s_waitcnt lgkmcnt(0)
	v_mfma_f32_16x16x32_bf16 v[62:65], v[152:155], v[184:187], v[62:65]
	v_mfma_f32_16x16x32_bf16 v[54:57], v[160:163], v[184:187], v[54:57]
	v_mfma_f32_16x16x32_bf16 v[46:49], v[152:155], v[204:207], v[46:49]
	v_mfma_f32_16x16x32_bf16 v[38:41], v[160:163], v[204:207], v[38:41]
	v_mfma_f32_16x16x32_bf16 v[24:27], v[152:155], v[212:215], v[24:27]
	v_mfma_f32_16x16x32_bf16 v[16:19], v[160:163], v[212:215], v[16:19]
	v_mfma_f32_16x16x32_bf16 v[8:11], v[152:155], v[220:223], v[8:11]
	v_mfma_f32_16x16x32_bf16 v[0:3], v[160:163], v[220:223], v[0:3]
	v_mfma_f32_16x16x32_bf16 v[62:65], v[156:159], v[188:191], v[62:65]
	v_mfma_f32_16x16x32_bf16 v[54:57], v[164:167], v[188:191], v[54:57]
	v_mfma_f32_16x16x32_bf16 v[46:49], v[156:159], v[208:211], v[46:49]
	v_mfma_f32_16x16x32_bf16 v[38:41], v[164:167], v[208:211], v[38:41]
	v_mfma_f32_16x16x32_bf16 v[24:27], v[156:159], v[216:219], v[24:27]
	v_mfma_f32_16x16x32_bf16 v[16:19], v[164:167], v[216:219], v[16:19]
	v_mfma_f32_16x16x32_bf16 v[8:11], v[156:159], v[224:227], v[8:11]
	v_mfma_f32_16x16x32_bf16 v[0:3], v[164:167], v[224:227], v[0:3]
	s_setprio 0
	s_setprio 1
	v_mfma_f32_16x16x32_bf16 v[58:61], v[168:171], v[184:187], v[58:61]
	v_mfma_f32_16x16x32_bf16 v[50:53], v[176:179], v[184:187], v[50:53]
	v_mfma_f32_16x16x32_bf16 v[42:45], v[168:171], v[204:207], v[42:45]
	v_mfma_f32_16x16x32_bf16 v[28:31], v[176:179], v[204:207], v[28:31]
	v_mfma_f32_16x16x32_bf16 v[34:37], v[168:171], v[212:215], v[34:37]
	v_mfma_f32_16x16x32_bf16 v[20:23], v[176:179], v[212:215], v[20:23]
	v_mfma_f32_16x16x32_bf16 v[12:15], v[168:171], v[220:223], v[12:15]
	v_mfma_f32_16x16x32_bf16 v[4:7], v[176:179], v[220:223], v[4:7]
	v_mfma_f32_16x16x32_bf16 v[58:61], v[172:175], v[188:191], v[58:61]
	v_mfma_f32_16x16x32_bf16 v[50:53], v[180:183], v[188:191], v[50:53]
	v_mfma_f32_16x16x32_bf16 v[42:45], v[172:175], v[208:211], v[42:45]
	v_mfma_f32_16x16x32_bf16 v[28:31], v[180:183], v[208:211], v[28:31]
	v_mfma_f32_16x16x32_bf16 v[34:37], v[172:175], v[216:219], v[34:37]
	v_mfma_f32_16x16x32_bf16 v[20:23], v[180:183], v[216:219], v[20:23]
	v_mfma_f32_16x16x32_bf16 v[12:15], v[172:175], v[224:227], v[12:15]
	v_mfma_f32_16x16x32_bf16 v[4:7], v[180:183], v[224:227], v[4:7]
	s_setprio 0
	s_barrier
	v_add_u32_e32 v164, 0x18000, v138
	v_add_u32_e32 v180, 0x1c000, v138
	ds_read_b128 v[152:155], v164
	ds_read_b128 v[156:159], v164 offset:1024
	ds_read_b128 v[160:163], v164 offset:2048
	ds_read_b128 v[164:167], v164 offset:3072
	ds_read_b128 v[168:171], v180
	ds_read_b128 v[172:175], v180 offset:1024
	ds_read_b128 v[176:179], v180 offset:2048
	ds_read_b128 v[180:183], v180 offset:3072
	s_add_u32 s6, s34, 0x40000
	s_addc_u32 s7, s35, 0
	v_readfirstlane_b32 s10, v144
	v_lshl_add_u64 v[232:233], s[6:7], 0, v[32:33]
	s_mov_b32 m0, s10
	ds_read_b128 v[184:187], v137 offset:32768
	ds_read_b128 v[188:191], v137 offset:33792
	ds_read_b128 v[204:207], v137 offset:34816
	ds_read_b128 v[208:211], v137 offset:35840
	ds_read_b128 v[212:215], v137 offset:36864
	ds_read_b128 v[216:219], v137 offset:37888
	ds_read_b128 v[220:223], v137 offset:38912
	ds_read_b128 v[224:227], v137 offset:39936
	global_load_lds_dwordx4 v[232:233], off
	v_lshl_add_u64 v[232:233], s[6:7], 0, v[130:131]
	v_readfirstlane_b32 s6, v145
	s_mov_b32 m0, s6
	s_nop 0
	global_load_lds_dwordx4 v[232:233], off
	s_waitcnt vmcnt(8)
	s_waitcnt lgkmcnt(0)
	s_barrier
	s_setprio 1
	s_waitcnt lgkmcnt(0)
	v_mfma_f32_16x16x32_bf16 v[126:129], v[152:155], v[184:187], v[126:129]
	v_mfma_f32_16x16x32_bf16 v[118:121], v[160:163], v[184:187], v[118:121]
	v_mfma_f32_16x16x32_bf16 v[110:113], v[152:155], v[204:207], v[110:113]
	v_mfma_f32_16x16x32_bf16 v[102:105], v[160:163], v[204:207], v[102:105]
	v_mfma_f32_16x16x32_bf16 v[94:97], v[152:155], v[212:215], v[94:97]
	v_mfma_f32_16x16x32_bf16 v[86:89], v[160:163], v[212:215], v[86:89]
	v_mfma_f32_16x16x32_bf16 v[78:81], v[152:155], v[220:223], v[78:81]
	v_mfma_f32_16x16x32_bf16 v[70:73], v[160:163], v[220:223], v[70:73]
	v_mfma_f32_16x16x32_bf16 v[126:129], v[156:159], v[188:191], v[126:129]
	v_mfma_f32_16x16x32_bf16 v[118:121], v[164:167], v[188:191], v[118:121]
	v_mfma_f32_16x16x32_bf16 v[110:113], v[156:159], v[208:211], v[110:113]
	v_mfma_f32_16x16x32_bf16 v[102:105], v[164:167], v[208:211], v[102:105]
	v_mfma_f32_16x16x32_bf16 v[94:97], v[156:159], v[216:219], v[94:97]
	v_mfma_f32_16x16x32_bf16 v[86:89], v[164:167], v[216:219], v[86:89]
	v_mfma_f32_16x16x32_bf16 v[78:81], v[156:159], v[224:227], v[78:81]
	v_mfma_f32_16x16x32_bf16 v[70:73], v[164:167], v[224:227], v[70:73]
	s_setprio 0
	s_setprio 1
	v_mfma_f32_16x16x32_bf16 v[122:125], v[168:171], v[184:187], v[122:125]
	v_mfma_f32_16x16x32_bf16 v[114:117], v[176:179], v[184:187], v[114:117]
	v_mfma_f32_16x16x32_bf16 v[106:109], v[168:171], v[204:207], v[106:109]
	v_mfma_f32_16x16x32_bf16 v[98:101], v[176:179], v[204:207], v[98:101]
	v_mfma_f32_16x16x32_bf16 v[90:93], v[168:171], v[212:215], v[90:93]
	v_mfma_f32_16x16x32_bf16 v[82:85], v[176:179], v[212:215], v[82:85]
	v_mfma_f32_16x16x32_bf16 v[74:77], v[168:171], v[220:223], v[74:77]
	v_mfma_f32_16x16x32_bf16 v[66:69], v[176:179], v[220:223], v[66:69]
	v_mfma_f32_16x16x32_bf16 v[122:125], v[172:175], v[188:191], v[122:125]
	v_mfma_f32_16x16x32_bf16 v[114:117], v[180:183], v[188:191], v[114:117]
	v_mfma_f32_16x16x32_bf16 v[106:109], v[172:175], v[208:211], v[106:109]
	v_mfma_f32_16x16x32_bf16 v[98:101], v[180:183], v[208:211], v[98:101]
	v_mfma_f32_16x16x32_bf16 v[90:93], v[172:175], v[216:219], v[90:93]
	v_mfma_f32_16x16x32_bf16 v[82:85], v[180:183], v[216:219], v[82:85]
	v_mfma_f32_16x16x32_bf16 v[74:77], v[172:175], v[224:227], v[74:77]
	v_mfma_f32_16x16x32_bf16 v[66:69], v[180:183], v[224:227], v[66:69]
	s_setprio 0
	s_barrier
; #define STAGE(bufoff, GB) do { const char* g_ = (GB); \
;         _Pragma("unroll") for (int i_ = 0; i_ < 2; ++i_) __builtin_amdgcn_global_load_lds((const unsigned*)(g_ + voff[i_]), (LAS3 unsigned*)(L + (bufoff) + stoff + i_ * 8192), 16, 0, 0); } while (0)
; #define LDA(dst, b, h) do { _Pragma("unroll") for (int m = 0; m < 4; ++m) _Pragma("unroll") for (int k = 0; k < 2; ++k) dst[m][k] = *(const LAS3 bf16x8*)(L + SA(b, h) + aoff + m * 2048 + k * 1024); } while (0)
; #define WAIT_V(n) asm volatile("s_waitcnt vmcnt(" #n ")" ::: "memory")
; #define WAIT_L(n) asm volatile("s_waitcnt lgkmcnt(" #n ")" ::: "memory")
; #define BAR __builtin_amdgcn_s_barrier()
; #define SCHED __builtin_amdgcn_sched_barrier(0)
; template <int EPI>
; DI void gemm_phase(const bf16_t* __restrict__ A, const bf16_t* __restrict__ Bt, const int K, const int N, const Params& p, const int layer_j, char* lds) {
;     ...
;             WAIT_V(8); WAIT_L(0); BAR; MMA(0, 0, At, B0); MMA(0, 1, At, B1); BAR; SCHED;
;             LDA(At, 1, 1); STAGE(SB(1, 0), b3); STAGE(SB(1, 1), b3 + hstep); STAGE(SA(1, 0), a3);
;             WAIT_V(8); WAIT_L(0); BAR; MMA(1, 0, At, B0); MMA(1, 1, At, B1); BAR; SCHED;
;         }
	v_readfirstlane_b32 s6, v146
	v_lshl_add_u64 v[192:193], v[192:193], 0, s[94:95]
	s_mov_b32 m0, s6
	v_readfirstlane_b32 s6, v147
	ds_read_b128 v[184:187], v137 offset:49152
	ds_read_b128 v[188:191], v137 offset:50176
	ds_read_b128 v[204:207], v137 offset:51200
	ds_read_b128 v[208:211], v137 offset:52224
	ds_read_b128 v[212:215], v137 offset:53248
	ds_read_b128 v[216:219], v137 offset:54272
	ds_read_b128 v[220:223], v137 offset:55296
	ds_read_b128 v[224:227], v137 offset:56320
	global_load_lds_dwordx4 v[192:193], off
	s_mov_b32 m0, s6
	s_add_u32 s6, s30, 0x40080
	v_lshl_add_u64 v[192:193], v[194:195], 0, s[94:95]
	s_addc_u32 s7, s31, 0
	v_readfirstlane_b32 s10, v150
	global_load_lds_dwordx4 v[192:193], off
	v_lshl_add_u64 v[192:193], s[6:7], 0, v[32:33]
	s_mov_b32 m0, s10
	s_nop 0
	global_load_lds_dwordx4 v[192:193], off
	v_lshl_add_u64 v[192:193], s[6:7], 0, v[130:131]
	v_readfirstlane_b32 s6, v151
	s_mov_b32 m0, s6
	v_readfirstlane_b32 s6, v148
	global_load_lds_dwordx4 v[192:193], off
	v_lshl_add_u64 v[192:193], v[228:229], 0, s[94:95]
	s_mov_b32 m0, s6
	v_readfirstlane_b32 s6, v149
	global_load_lds_dwordx4 v[192:193], off
	v_lshl_add_u64 v[192:193], v[230:231], 0, s[94:95]
	s_mov_b32 m0, s6
	s_nop 0
	global_load_lds_dwordx4 v[192:193], off
	s_waitcnt vmcnt(8)
	s_waitcnt lgkmcnt(0)
	s_barrier
	s_setprio 1
	s_waitcnt lgkmcnt(0)
	v_mfma_f32_16x16x32_bf16 v[62:65], v[152:155], v[184:187], v[62:65]
	v_mfma_f32_16x16x32_bf16 v[54:57], v[160:163], v[184:187], v[54:57]
	v_mfma_f32_16x16x32_bf16 v[46:49], v[152:155], v[204:207], v[46:49]
	v_mfma_f32_16x16x32_bf16 v[38:41], v[160:163], v[204:207], v[38:41]
	v_mfma_f32_16x16x32_bf16 v[24:27], v[152:155], v[212:215], v[24:27]
	v_mfma_f32_16x16x32_bf16 v[16:19], v[160:163], v[212:215], v[16:19]
	v_mfma_f32_16x16x32_bf16 v[8:11], v[152:155], v[220:223], v[8:11]
	v_mfma_f32_16x16x32_bf16 v[0:3], v[160:163], v[220:223], v[0:3]
	v_mfma_f32_16x16x32_bf16 v[62:65], v[156:159], v[188:191], v[62:65]
	v_mfma_f32_16x16x32_bf16 v[54:57], v[164:167], v[188:191], v[54:57]
	v_mfma_f32_16x16x32_bf16 v[46:49], v[156:159], v[208:211], v[46:49]
	v_mfma_f32_16x16x32_bf16 v[38:41], v[164:167], v[208:211], v[38:41]
	v_mfma_f32_16x16x32_bf16 v[24:27], v[156:159], v[216:219], v[24:27]
	v_mfma_f32_16x16x32_bf16 v[16:19], v[164:167], v[216:219], v[16:19]
	v_mfma_f32_16x16x32_bf16 v[8:11], v[156:159], v[224:227], v[8:11]
	v_mfma_f32_16x16x32_bf16 v[0:3], v[164:167], v[224:227], v[0:3]
	s_setprio 0
	s_setprio 1
	v_mfma_f32_16x16x32_bf16 v[58:61], v[168:171], v[184:187], v[58:61]
	v_mfma_f32_16x16x32_bf16 v[50:53], v[176:179], v[184:187], v[50:53]
	v_mfma_f32_16x16x32_bf16 v[42:45], v[168:171], v[204:207], v[42:45]
	v_mfma_f32_16x16x32_bf16 v[28:31], v[176:179], v[204:207], v[28:31]
	v_mfma_f32_16x16x32_bf16 v[34:37], v[168:171], v[212:215], v[34:37]
	v_mfma_f32_16x16x32_bf16 v[20:23], v[176:179], v[212:215], v[20:23]
	v_mfma_f32_16x16x32_bf16 v[12:15], v[168:171], v[220:223], v[12:15]
	v_mfma_f32_16x16x32_bf16 v[4:7], v[176:179], v[220:223], v[4:7]
	v_mfma_f32_16x16x32_bf16 v[58:61], v[172:175], v[188:191], v[58:61]
	v_mfma_f32_16x16x32_bf16 v[50:53], v[180:183], v[188:191], v[50:53]
	v_mfma_f32_16x16x32_bf16 v[42:45], v[172:175], v[208:211], v[42:45]
	v_mfma_f32_16x16x32_bf16 v[28:31], v[180:183], v[208:211], v[28:31]
	v_mfma_f32_16x16x32_bf16 v[34:37], v[172:175], v[216:219], v[34:37]
	v_mfma_f32_16x16x32_bf16 v[20:23], v[180:183], v[216:219], v[20:23]
	v_mfma_f32_16x16x32_bf16 v[12:15], v[172:175], v[224:227], v[12:15]
	v_mfma_f32_16x16x32_bf16 v[4:7], v[180:183], v[224:227], v[4:7]
	s_setprio 0
	s_barrier
	s_add_i32 s37, s37, 2
	s_add_u32 s28, s28, 0x100
	s_addc_u32 s29, s29, 0
	s_cmp_gt_u32 s37, 13
	s_cbranch_scc0 .LBB0_43
	v_readlane_b32 s6, v254, 12
	v_readlane_b32 s7, v254, 13
	s_and_b64 vcc, exec, s[6:7]
	s_cbranch_vccz .LBB0_46
	s_barrier

; #define STAGE(bufoff, GB) do { const char* g_ = (GB); \
;         _Pragma("unroll") for (int i_ = 0; i_ < 2; ++i_) __builtin_amdgcn_global_load_lds((const unsigned*)(g_ + voff[i_]), (LAS3 unsigned*)(L + (bufoff) + stoff + i_ * 8192), 16, 0, 0); } while (0)
; #define LDA(dst, b, h) do { _Pragma("unroll") for (int m = 0; m < 4; ++m) _Pragma("unroll") for (int k = 0; k < 2; ++k) dst[m][k] = *(const LAS3 bf16x8*)(L + SA(b, h) + aoff + m * 2048 + k * 1024); } while (0)
; #define LDB(dst, b, h) do { _Pragma("unroll") for (int n = 0; n < 2; ++n) _Pragma("unroll") for (int k = 0; k < 2; ++k) dst[n][k] = *(const LAS3 bf16x8*)(L + SB(b, h) + boff + n * 2048 + k * 1024); } while (0)
; #define WAIT_V(n) asm volatile("s_waitcnt vmcnt(" #n ")" ::: "memory")
; #define WAIT_L(n) asm volatile("s_waitcnt lgkmcnt(" #n ")" ::: "memory")
; #define BAR __builtin_amdgcn_s_barrier()
; #define SCHED __builtin_amdgcn_sched_barrier(0)
; template <int EPI>
; DI void gemm_phase(const bf16_t* __restrict__ A, const bf16_t* __restrict__ Bt, const int K, const int N, const Params& p, const int layer_j, char* lds) {
;     ...
;         for (int t = 0; t < nt; t += 2) {
;             const bool last = (t == nt - 2);
;             const char* a1 = cA + (size_t)(t + 1) * kstep;
;             const char* a2 = last ? nA : cA + (size_t)(t + 2) * kstep; const char* b2 = last ? nB : cB + (size_t)(t + 2) * kstep;
;             const char* a3 = a2 + kstep; const char* b3 = b2 + kstep;
;             LDB(B0, 0, 0); LDB(B1, 0, 1); SCHED; LDA(At, 0, 0); STAGE(SA(1, 1), a1 + hstep);
;             WAIT_V(8); WAIT_L(0); BAR; MMA(0, 0, At, B0); MMA(0, 1, At, B1); BAR; SCHED;
;             LDA(At, 0, 1); STAGE(SB(0, 0), b2); STAGE(SB(0, 1), b2 + hstep); STAGE(SA(0, 0), a2);
;             WAIT_V(8); WAIT_L(0); BAR; MMA(1, 0, At, B0); MMA(1, 1, At, B1); BAR; SCHED;
.LBB0_106:
	v_add_u32_e32 v164, 0x10000, v138
	v_add_u32_e32 v180, 0x14000, v138
	ds_read_b128 v[152:155], v164
	ds_read_b128 v[156:159], v164 offset:1024
	ds_read_b128 v[160:163], v164 offset:2048
	ds_read_b128 v[164:167], v164 offset:3072
	ds_read_b128 v[168:171], v180
	ds_read_b128 v[172:175], v180 offset:1024
	ds_read_b128 v[176:179], v180 offset:2048
	ds_read_b128 v[180:183], v180 offset:3072
	s_add_i32 s39, s18, 2
	s_add_u32 s64, s16, 0x80
	s_addc_u32 s19, s17, 0
	s_cmp_eq_u32 s25, s18
	s_cselect_b32 s18, s14, s64
	s_cselect_b32 s19, s15, s19
	s_cselect_b32 s65, s36, s38
	s_cselect_b32 s64, s35, s37
	v_add_u32_e32 v194, 0xc000, v136
	v_lshl_add_u64 v[192:193], s[16:17], 0, v[134:135]
	v_readfirstlane_b32 s66, v194
	v_add_u32_e32 v194, 0xe000, v136
	s_mov_b32 m0, s66
	v_readfirstlane_b32 s66, v194
	ds_read_b128 v[184:187], v137
	ds_read_b128 v[188:191], v137 offset:1024
	ds_read_b128 v[204:207], v137 offset:2048
	ds_read_b128 v[208:211], v137 offset:3072
	ds_read_b128 v[212:215], v137 offset:4096
	ds_read_b128 v[216:219], v137 offset:5120
	ds_read_b128 v[220:223], v137 offset:6144
	ds_read_b128 v[224:227], v137 offset:7168
	global_load_lds_dwordx4 v[192:193], off
	v_lshl_add_u64 v[192:193], s[16:17], 0, v[132:133]
	s_mov_b32 m0, s66
	s_nop 0
	global_load_lds_dwordx4 v[192:193], off
	s_waitcnt vmcnt(8)
	s_waitcnt lgkmcnt(0)
	s_barrier
	s_setprio 1
	s_waitcnt lgkmcnt(0)
	v_mfma_f32_16x16x32_bf16 v[126:129], v[184:187], v[152:155], v[126:129]
	v_mfma_f32_16x16x32_bf16 v[122:125], v[184:187], v[160:163], v[122:125]
	v_mfma_f32_16x16x32_bf16 v[110:113], v[204:207], v[152:155], v[110:113]
	v_mfma_f32_16x16x32_bf16 v[106:109], v[204:207], v[160:163], v[106:109]
	v_mfma_f32_16x16x32_bf16 v[94:97], v[212:215], v[152:155], v[94:97]
	v_mfma_f32_16x16x32_bf16 v[90:93], v[212:215], v[160:163], v[90:93]
	v_mfma_f32_16x16x32_bf16 v[78:81], v[220:223], v[152:155], v[78:81]
	v_mfma_f32_16x16x32_bf16 v[74:77], v[220:223], v[160:163], v[74:77]
	v_mfma_f32_16x16x32_bf16 v[126:129], v[188:191], v[156:159], v[126:129]
	v_mfma_f32_16x16x32_bf16 v[122:125], v[188:191], v[164:167], v[122:125]
	v_mfma_f32_16x16x32_bf16 v[110:113], v[208:211], v[156:159], v[110:113]
	v_mfma_f32_16x16x32_bf16 v[106:109], v[208:211], v[164:167], v[106:109]
	v_mfma_f32_16x16x32_bf16 v[94:97], v[216:219], v[156:159], v[94:97]
	v_mfma_f32_16x16x32_bf16 v[90:93], v[216:219], v[164:167], v[90:93]
	v_mfma_f32_16x16x32_bf16 v[78:81], v[224:227], v[156:159], v[78:81]
	v_mfma_f32_16x16x32_bf16 v[74:77], v[224:227], v[164:167], v[74:77]
	s_setprio 0
	s_setprio 1
	v_mfma_f32_16x16x32_bf16 v[118:121], v[184:187], v[168:171], v[118:121]
	v_mfma_f32_16x16x32_bf16 v[114:117], v[184:187], v[176:179], v[114:117]
	v_mfma_f32_16x16x32_bf16 v[102:105], v[204:207], v[168:171], v[102:105]
	v_mfma_f32_16x16x32_bf16 v[98:101], v[204:207], v[176:179], v[98:101]
	v_mfma_f32_16x16x32_bf16 v[86:89], v[212:215], v[168:171], v[86:89]
	v_mfma_f32_16x16x32_bf16 v[82:85], v[212:215], v[176:179], v[82:85]
	v_mfma_f32_16x16x32_bf16 v[70:73], v[220:223], v[168:171], v[70:73]
	v_mfma_f32_16x16x32_bf16 v[66:69], v[220:223], v[176:179], v[66:69]
	v_mfma_f32_16x16x32_bf16 v[118:121], v[188:191], v[172:175], v[118:121]
	v_mfma_f32_16x16x32_bf16 v[114:117], v[188:191], v[180:183], v[114:117]
	v_mfma_f32_16x16x32_bf16 v[102:105], v[208:211], v[172:175], v[102:105]
	v_mfma_f32_16x16x32_bf16 v[98:101], v[208:211], v[180:183], v[98:101]
	v_mfma_f32_16x16x32_bf16 v[86:89], v[216:219], v[172:175], v[86:89]
	v_mfma_f32_16x16x32_bf16 v[82:85], v[216:219], v[180:183], v[82:85]
	v_mfma_f32_16x16x32_bf16 v[70:73], v[224:227], v[172:175], v[70:73]
	v_mfma_f32_16x16x32_bf16 v[66:69], v[224:227], v[180:183], v[66:69]
	s_setprio 0
	s_barrier
	v_readfirstlane_b32 s66, v139
	v_lshl_add_u64 v[192:193], s[64:65], 0, v[32:33]
	s_mov_b32 m0, s66
	v_lshl_add_u64 v[194:195], s[64:65], 0, v[130:131]
	v_readfirstlane_b32 s66, v140
	s_add_u32 s64, s64, s88
	ds_read_b128 v[184:187], v137 offset:16384
	ds_read_b128 v[188:191], v137 offset:17408
	ds_read_b128 v[204:207], v137 offset:18432
	ds_read_b128 v[208:211], v137 offset:19456
	ds_read_b128 v[212:215], v137 offset:20480
	ds_read_b128 v[216:219], v137 offset:21504
	ds_read_b128 v[220:223], v137 offset:22528
	ds_read_b128 v[224:227], v137 offset:23552
	global_load_lds_dwordx4 v[192:193], off
	s_mov_b32 m0, s66
	s_addc_u32 s65, s65, 0
	v_readfirstlane_b32 s66, v141
	global_load_lds_dwordx4 v[194:195], off
	v_lshl_add_u64 v[228:229], s[64:65], 0, v[32:33]
	s_mov_b32 m0, s66
	v_lshl_add_u64 v[230:231], s[64:65], 0, v[130:131]
	v_readfirstlane_b32 s64, v142
	global_load_lds_dwordx4 v[228:229], off
	s_mov_b32 m0, s64
	v_readfirstlane_b32 s64, v136
	global_load_lds_dwordx4 v[230:231], off
	v_lshl_add_u64 v[232:233], s[18:19], 0, v[32:33]
	s_mov_b32 m0, s64
	v_readfirstlane_b32 s64, v143
	global_load_lds_dwordx4 v[232:233], off
	v_lshl_add_u64 v[234:235], s[18:19], 0, v[130:131]
	s_mov_b32 m0, s64
	s_nop 0
	global_load_lds_dwordx4 v[234:235], off
	s_waitcnt vmcnt(8)
	s_waitcnt lgkmcnt(0)
	s_barrier
; #define STAGE(bufoff, GB) do { const char* g_ = (GB); \
;         _Pragma("unroll") for (int i_ = 0; i_ < 2; ++i_) __builtin_amdgcn_global_load_lds((const unsigned*)(g_ + voff[i_]), (LAS3 unsigned*)(L + (bufoff) + stoff + i_ * 8192), 16, 0, 0); } while (0)
; #define LDA(dst, b, h) do { _Pragma("unroll") for (int m = 0; m < 4; ++m) _Pragma("unroll") for (int k = 0; k < 2; ++k) dst[m][k] = *(const LAS3 bf16x8*)(L + SA(b, h) + aoff + m * 2048 + k * 1024); } while (0)
; #define LDB(dst, b, h) do { _Pragma("unroll") for (int n = 0; n < 2; ++n) _Pragma("unroll") for (int k = 0; k < 2; ++k) dst[n][k] = *(const LAS3 bf16x8*)(L + SB(b, h) + boff + n * 2048 + k * 1024); } while (0)
; #define WAIT_V(n) asm volatile("s_waitcnt vmcnt(" #n ")" ::: "memory")
; #define WAIT_L(n) asm volatile("s_waitcnt lgkmcnt(" #n ")" ::: "memory")
; #define BAR __builtin_amdgcn_s_barrier()
; #define SCHED __builtin_amdgcn_sched_barrier(0)
; template <int EPI>
; DI void gemm_phase(const bf16_t* __restrict__ A, const bf16_t* __restrict__ Bt, const int K, const int N, const Params& p, const int layer_j, char* lds) {
;     ...
;             WAIT_V(8); WAIT_L(0); BAR; MMA(1, 0, At, B0); MMA(1, 1, At, B1); BAR; SCHED;
;             LDB(B0, 1, 0); LDB(B1, 1, 1); SCHED; LDA(At, 1, 0); STAGE(SA(0, 1), a2 + hstep);
;             WAIT_V(8); WAIT_L(0); BAR; MMA(0, 0, At, B0); MMA(0, 1, At, B1); BAR; SCHED;
;             LDA(At, 1, 1); STAGE(SB(1, 0), b3); STAGE(SB(1, 1), b3 + hstep); STAGE(SA(1, 0), a3);
;             WAIT_V(8); WAIT_L(0); BAR; MMA(1, 0, At, B0); MMA(1, 1, At, B1); BAR; SCHED;
	s_setprio 1
	s_waitcnt lgkmcnt(0)
	v_mfma_f32_16x16x32_bf16 v[62:65], v[184:187], v[152:155], v[62:65]
	v_mfma_f32_16x16x32_bf16 v[58:61], v[184:187], v[160:163], v[58:61]
	v_mfma_f32_16x16x32_bf16 v[38:41], v[204:207], v[152:155], v[38:41]
	v_mfma_f32_16x16x32_bf16 v[24:27], v[204:207], v[160:163], v[24:27]
	v_mfma_f32_16x16x32_bf16 v[12:15], v[212:215], v[152:155], v[12:15]
	v_mfma_f32_16x16x32_bf16 v[8:11], v[212:215], v[160:163], v[8:11]
	v_mfma_f32_16x16x32_bf16 v[4:7], v[220:223], v[152:155], v[4:7]
	v_mfma_f32_16x16x32_bf16 v[0:3], v[220:223], v[160:163], v[0:3]
	v_mfma_f32_16x16x32_bf16 v[62:65], v[188:191], v[156:159], v[62:65]
	v_mfma_f32_16x16x32_bf16 v[58:61], v[188:191], v[164:167], v[58:61]
	v_mfma_f32_16x16x32_bf16 v[38:41], v[208:211], v[156:159], v[38:41]
	v_mfma_f32_16x16x32_bf16 v[24:27], v[208:211], v[164:167], v[24:27]
	v_mfma_f32_16x16x32_bf16 v[12:15], v[216:219], v[156:159], v[12:15]
	v_mfma_f32_16x16x32_bf16 v[8:11], v[216:219], v[164:167], v[8:11]
	v_mfma_f32_16x16x32_bf16 v[4:7], v[224:227], v[156:159], v[4:7]
	v_mfma_f32_16x16x32_bf16 v[0:3], v[224:227], v[164:167], v[0:3]
	s_setprio 0
	s_setprio 1
	v_mfma_f32_16x16x32_bf16 v[46:49], v[184:187], v[168:171], v[46:49]
	v_mfma_f32_16x16x32_bf16 v[42:45], v[184:187], v[176:179], v[42:45]
	v_mfma_f32_16x16x32_bf16 v[20:23], v[204:207], v[168:171], v[20:23]
	v_mfma_f32_16x16x32_bf16 v[16:19], v[204:207], v[176:179], v[16:19]
	v_mfma_f32_16x16x32_bf16 v[50:53], v[212:215], v[168:171], v[50:53]
	v_mfma_f32_16x16x32_bf16 v[54:57], v[212:215], v[176:179], v[54:57]
	v_mfma_f32_16x16x32_bf16 v[28:31], v[220:223], v[168:171], v[28:31]
	v_mfma_f32_16x16x32_bf16 v[34:37], v[220:223], v[176:179], v[34:37]
	v_mfma_f32_16x16x32_bf16 v[46:49], v[188:191], v[172:175], v[46:49]
	v_mfma_f32_16x16x32_bf16 v[42:45], v[188:191], v[180:183], v[42:45]
	v_mfma_f32_16x16x32_bf16 v[20:23], v[208:211], v[172:175], v[20:23]
	v_mfma_f32_16x16x32_bf16 v[16:19], v[208:211], v[180:183], v[16:19]
	v_mfma_f32_16x16x32_bf16 v[50:53], v[216:219], v[172:175], v[50:53]
	v_mfma_f32_16x16x32_bf16 v[54:57], v[216:219], v[180:183], v[54:57]
	v_mfma_f32_16x16x32_bf16 v[28:31], v[224:227], v[172:175], v[28:31]
	v_mfma_f32_16x16x32_bf16 v[34:37], v[224:227], v[180:183], v[34:37]
	s_setprio 0
	s_barrier
	v_add_u32_e32 v164, 0x18000, v138
	v_add_u32_e32 v180, 0x1c000, v138
	ds_read_b128 v[152:155], v164
	ds_read_b128 v[156:159], v164 offset:1024
	ds_read_b128 v[160:163], v164 offset:2048
	ds_read_b128 v[164:167], v164 offset:3072
	ds_read_b128 v[168:171], v180
	ds_read_b128 v[172:175], v180 offset:1024
	ds_read_b128 v[176:179], v180 offset:2048
	ds_read_b128 v[180:183], v180 offset:3072
	s_add_u32 s18, s18, s88
	s_addc_u32 s19, s19, 0
	v_readfirstlane_b32 s64, v144
	v_lshl_add_u64 v[236:237], s[18:19], 0, v[32:33]
	s_mov_b32 m0, s64
	ds_read_b128 v[184:187], v137 offset:32768
	ds_read_b128 v[188:191], v137 offset:33792
	ds_read_b128 v[204:207], v137 offset:34816
	ds_read_b128 v[208:211], v137 offset:35840
	ds_read_b128 v[212:215], v137 offset:36864
	ds_read_b128 v[216:219], v137 offset:37888
	ds_read_b128 v[220:223], v137 offset:38912
	ds_read_b128 v[224:227], v137 offset:39936
	global_load_lds_dwordx4 v[236:237], off
	v_lshl_add_u64 v[236:237], s[18:19], 0, v[130:131]
	v_readfirstlane_b32 s18, v145
	s_mov_b32 m0, s18
	s_nop 0
	global_load_lds_dwordx4 v[236:237], off
	s_waitcnt vmcnt(8)
	s_waitcnt lgkmcnt(0)
	s_barrier
	s_setprio 1
	s_waitcnt lgkmcnt(0)
	v_mfma_f32_16x16x32_bf16 v[126:129], v[184:187], v[152:155], v[126:129]
	v_mfma_f32_16x16x32_bf16 v[122:125], v[184:187], v[160:163], v[122:125]
	v_mfma_f32_16x16x32_bf16 v[110:113], v[204:207], v[152:155], v[110:113]
	v_mfma_f32_16x16x32_bf16 v[106:109], v[204:207], v[160:163], v[106:109]
	v_mfma_f32_16x16x32_bf16 v[94:97], v[212:215], v[152:155], v[94:97]
	v_mfma_f32_16x16x32_bf16 v[90:93], v[212:215], v[160:163], v[90:93]
	v_mfma_f32_16x16x32_bf16 v[78:81], v[220:223], v[152:155], v[78:81]
	v_mfma_f32_16x16x32_bf16 v[74:77], v[220:223], v[160:163], v[74:77]
	v_mfma_f32_16x16x32_bf16 v[126:129], v[188:191], v[156:159], v[126:129]
	v_mfma_f32_16x16x32_bf16 v[122:125], v[188:191], v[164:167], v[122:125]
	v_mfma_f32_16x16x32_bf16 v[110:113], v[208:211], v[156:159], v[110:113]
	v_mfma_f32_16x16x32_bf16 v[106:109], v[208:211], v[164:167], v[106:109]
	v_mfma_f32_16x16x32_bf16 v[94:97], v[216:219], v[156:159], v[94:97]
	v_mfma_f32_16x16x32_bf16 v[90:93], v[216:219], v[164:167], v[90:93]
	v_mfma_f32_16x16x32_bf16 v[78:81], v[224:227], v[156:159], v[78:81]
	v_mfma_f32_16x16x32_bf16 v[74:77], v[224:227], v[164:167], v[74:77]
	s_setprio 0
	s_setprio 1
	v_mfma_f32_16x16x32_bf16 v[118:121], v[184:187], v[168:171], v[118:121]
	v_mfma_f32_16x16x32_bf16 v[114:117], v[184:187], v[176:179], v[114:117]
	v_mfma_f32_16x16x32_bf16 v[102:105], v[204:207], v[168:171], v[102:105]
	v_mfma_f32_16x16x32_bf16 v[98:101], v[204:207], v[176:179], v[98:101]
	v_mfma_f32_16x16x32_bf16 v[86:89], v[212:215], v[168:171], v[86:89]
	v_mfma_f32_16x16x32_bf16 v[82:85], v[212:215], v[176:179], v[82:85]
	v_mfma_f32_16x16x32_bf16 v[70:73], v[220:223], v[168:171], v[70:73]
	v_mfma_f32_16x16x32_bf16 v[66:69], v[220:223], v[176:179], v[66:69]
	v_mfma_f32_16x16x32_bf16 v[118:121], v[188:191], v[172:175], v[118:121]
	v_mfma_f32_16x16x32_bf16 v[114:117], v[188:191], v[180:183], v[114:117]
	v_mfma_f32_16x16x32_bf16 v[102:105], v[208:211], v[172:175], v[102:105]
	v_mfma_f32_16x16x32_bf16 v[98:101], v[208:211], v[180:183], v[98:101]
	v_mfma_f32_16x16x32_bf16 v[86:89], v[216:219], v[172:175], v[86:89]
	v_mfma_f32_16x16x32_bf16 v[82:85], v[216:219], v[180:183], v[82:85]
	v_mfma_f32_16x16x32_bf16 v[70:73], v[224:227], v[172:175], v[70:73]
	v_mfma_f32_16x16x32_bf16 v[66:69], v[224:227], v[180:183], v[66:69]
	s_setprio 0
	s_barrier
; #define STAGE(bufoff, GB) do { const char* g_ = (GB); \
;         _Pragma("unroll") for (int i_ = 0; i_ < 2; ++i_) __builtin_amdgcn_global_load_lds((const unsigned*)(g_ + voff[i_]), (LAS3 unsigned*)(L + (bufoff) + stoff + i_ * 8192), 16, 0, 0); } while (0)
; #define LDA(dst, b, h) do { _Pragma("unroll") for (int m = 0; m < 4; ++m) _Pragma("unroll") for (int k = 0; k < 2; ++k) dst[m][k] = *(const LAS3 bf16x8*)(L + SA(b, h) + aoff + m * 2048 + k * 1024); } while (0)
; #define WAIT_V(n) asm volatile("s_waitcnt vmcnt(" #n ")" ::: "memory")
; #define WAIT_L(n) asm volatile("s_waitcnt lgkmcnt(" #n ")" ::: "memory")
; #define BAR __builtin_amdgcn_s_barrier()
; #define SCHED __builtin_amdgcn_sched_barrier(0)
; template <int EPI>
; DI void gemm_phase(const bf16_t* __restrict__ A, const bf16_t* __restrict__ Bt, const int K, const int N, const Params& p, const int layer_j, char* lds) {
;     ...
;             LDA(At, 1, 1); STAGE(SB(1, 0), b3); STAGE(SB(1, 1), b3 + hstep); STAGE(SA(1, 0), a3);
;             WAIT_V(8); WAIT_L(0); BAR; MMA(1, 0, At, B0); MMA(1, 1, At, B1); BAR; SCHED;
;         }
	v_readfirstlane_b32 s18, v146
	v_lshl_add_u64 v[192:193], v[192:193], 0, s[94:95]
	s_mov_b32 m0, s18
	v_readfirstlane_b32 s18, v147
	ds_read_b128 v[184:187], v137 offset:49152
	ds_read_b128 v[188:191], v137 offset:50176
	ds_read_b128 v[204:207], v137 offset:51200
	ds_read_b128 v[208:211], v137 offset:52224
	ds_read_b128 v[212:215], v137 offset:53248
	ds_read_b128 v[216:219], v137 offset:54272
	ds_read_b128 v[220:223], v137 offset:55296
	ds_read_b128 v[224:227], v137 offset:56320
	global_load_lds_dwordx4 v[192:193], off
	v_lshl_add_u64 v[192:193], v[194:195], 0, s[94:95]
	s_mov_b32 m0, s18
	v_readfirstlane_b32 s18, v150
	global_load_lds_dwordx4 v[192:193], off
	v_lshl_add_u64 v[192:193], v[228:229], 0, s[94:95]
	s_mov_b32 m0, s18
	v_readfirstlane_b32 s18, v151
	global_load_lds_dwordx4 v[192:193], off
	v_lshl_add_u64 v[192:193], v[230:231], 0, s[94:95]
	s_mov_b32 m0, s18
	v_readfirstlane_b32 s18, v148
	global_load_lds_dwordx4 v[192:193], off
	v_lshl_add_u64 v[192:193], v[232:233], 0, s[94:95]
	s_mov_b32 m0, s18
	v_readfirstlane_b32 s18, v149
	global_load_lds_dwordx4 v[192:193], off
	v_lshl_add_u64 v[192:193], v[234:235], 0, s[94:95]
	s_mov_b32 m0, s18
	s_nop 0
	global_load_lds_dwordx4 v[192:193], off
	s_waitcnt vmcnt(8)
	s_waitcnt lgkmcnt(0)
	s_barrier
	s_setprio 1
	s_waitcnt lgkmcnt(0)
	v_mfma_f32_16x16x32_bf16 v[62:65], v[184:187], v[152:155], v[62:65]
	v_mfma_f32_16x16x32_bf16 v[58:61], v[184:187], v[160:163], v[58:61]
	v_mfma_f32_16x16x32_bf16 v[38:41], v[204:207], v[152:155], v[38:41]
	v_mfma_f32_16x16x32_bf16 v[24:27], v[204:207], v[160:163], v[24:27]
	v_mfma_f32_16x16x32_bf16 v[12:15], v[212:215], v[152:155], v[12:15]
	v_mfma_f32_16x16x32_bf16 v[8:11], v[212:215], v[160:163], v[8:11]
	v_mfma_f32_16x16x32_bf16 v[4:7], v[220:223], v[152:155], v[4:7]
	v_mfma_f32_16x16x32_bf16 v[0:3], v[220:223], v[160:163], v[0:3]
	v_mfma_f32_16x16x32_bf16 v[62:65], v[188:191], v[156:159], v[62:65]
	v_mfma_f32_16x16x32_bf16 v[58:61], v[188:191], v[164:167], v[58:61]
	v_mfma_f32_16x16x32_bf16 v[38:41], v[208:211], v[156:159], v[38:41]
	v_mfma_f32_16x16x32_bf16 v[24:27], v[208:211], v[164:167], v[24:27]
	v_mfma_f32_16x16x32_bf16 v[12:15], v[216:219], v[156:159], v[12:15]
	v_mfma_f32_16x16x32_bf16 v[8:11], v[216:219], v[164:167], v[8:11]
	v_mfma_f32_16x16x32_bf16 v[4:7], v[224:227], v[156:159], v[4:7]
	v_mfma_f32_16x16x32_bf16 v[0:3], v[224:227], v[164:167], v[0:3]
	s_setprio 0
	s_setprio 1
	v_mfma_f32_16x16x32_bf16 v[46:49], v[184:187], v[168:171], v[46:49]
	v_mfma_f32_16x16x32_bf16 v[42:45], v[184:187], v[176:179], v[42:45]
	v_mfma_f32_16x16x32_bf16 v[20:23], v[204:207], v[168:171], v[20:23]
	v_mfma_f32_16x16x32_bf16 v[16:19], v[204:207], v[176:179], v[16:19]
	v_mfma_f32_16x16x32_bf16 v[50:53], v[212:215], v[168:171], v[50:53]
	v_mfma_f32_16x16x32_bf16 v[54:57], v[212:215], v[176:179], v[54:57]
	v_mfma_f32_16x16x32_bf16 v[28:31], v[220:223], v[168:171], v[28:31]
	v_mfma_f32_16x16x32_bf16 v[34:37], v[220:223], v[176:179], v[34:37]
	v_mfma_f32_16x16x32_bf16 v[46:49], v[188:191], v[172:175], v[46:49]
	v_mfma_f32_16x16x32_bf16 v[42:45], v[188:191], v[180:183], v[42:45]
	v_mfma_f32_16x16x32_bf16 v[20:23], v[208:211], v[172:175], v[20:23]
	v_mfma_f32_16x16x32_bf16 v[16:19], v[208:211], v[180:183], v[16:19]
	v_mfma_f32_16x16x32_bf16 v[50:53], v[216:219], v[172:175], v[50:53]
	v_mfma_f32_16x16x32_bf16 v[54:57], v[216:219], v[180:183], v[54:57]
	v_mfma_f32_16x16x32_bf16 v[28:31], v[224:227], v[172:175], v[28:31]
	v_mfma_f32_16x16x32_bf16 v[34:37], v[224:227], v[180:183], v[34:37]
	s_setprio 0
	s_barrier
	s_add_u32 s37, s37, 0x100
	s_addc_u32 s38, s38, 0
	s_add_u32 s16, s16, 0x100
	s_addc_u32 s17, s17, 0
	s_cmp_ge_u32 s39, s24
	s_mov_b32 s18, s39
	s_cbranch_scc0 .LBB0_106
	v_readlane_b32 s16, v254, 12
	v_readlane_b32 s17, v254, 13
	s_and_b64 vcc, exec, s[16:17]
	s_movk_i32 s37, 0x580
	s_cbranch_vccz .LBB0_109
	s_barrier

; #define STAGE(bufoff, GB) do { const char* g_ = (GB); \
;         _Pragma("unroll") for (int i_ = 0; i_ < 2; ++i_) __builtin_amdgcn_global_load_lds((const unsigned*)(g_ + voff[i_]), (LAS3 unsigned*)(L + (bufoff) + stoff + i_ * 8192), 16, 0, 0); } while (0)
; #define LDA(dst, b, h) do { _Pragma("unroll") for (int m = 0; m < 4; ++m) _Pragma("unroll") for (int k = 0; k < 2; ++k) dst[m][k] = *(const LAS3 bf16x8*)(L + SA(b, h) + aoff + m * 2048 + k * 1024); } while (0)
; #define LDB(dst, b, h) do { _Pragma("unroll") for (int n = 0; n < 2; ++n) _Pragma("unroll") for (int k = 0; k < 2; ++k) dst[n][k] = *(const LAS3 bf16x8*)(L + SB(b, h) + boff + n * 2048 + k * 1024); } while (0)
; #define WAIT_V(n) asm volatile("s_waitcnt vmcnt(" #n ")" ::: "memory")
; #define WAIT_L(n) asm volatile("s_waitcnt lgkmcnt(" #n ")" ::: "memory")
; #define BAR __builtin_amdgcn_s_barrier()
; #define SCHED __builtin_amdgcn_sched_barrier(0)
; template <int EPI>
; DI void gemm_phase(const bf16_t* __restrict__ A, const bf16_t* __restrict__ Bt, const int K, const int N, const Params& p, const int layer_j, char* lds) {
;     ...
;         for (int t = 0; t < nt; t += 2) {
;             const bool last = (t == nt - 2);
;             const char* a1 = cA + (size_t)(t + 1) * kstep;
;             const char* a2 = last ? nA : cA + (size_t)(t + 2) * kstep; const char* b2 = last ? nB : cB + (size_t)(t + 2) * kstep;
;             const char* a3 = a2 + kstep; const char* b3 = b2 + kstep;
;             LDB(B0, 0, 0); LDB(B1, 0, 1); SCHED; LDA(At, 0, 0); STAGE(SA(1, 1), a1 + hstep);
;             WAIT_V(8); WAIT_L(0); BAR; MMA(0, 0, At, B0); MMA(0, 1, At, B1); BAR; SCHED;
;             LDA(At, 0, 1); STAGE(SB(0, 0), b2); STAGE(SB(0, 1), b2 + hstep); STAGE(SA(0, 0), a2);
;             WAIT_V(8); WAIT_L(0); BAR; MMA(1, 0, At, B0); MMA(1, 1, At, B1); BAR; SCHED;
.LBB0_338:
	v_add_u32_e32 v148, 0x10000, v186
	v_add_u32_e32 v164, 0x14000, v186
	s_add_u32 s16, s87, s28
	ds_read_b128 v[136:139], v148
	ds_read_b128 v[140:143], v148 offset:1024
	ds_read_b128 v[144:147], v148 offset:2048
	ds_read_b128 v[148:151], v148 offset:3072
	ds_read_b128 v[152:155], v164
	ds_read_b128 v[156:159], v164 offset:1024
	ds_read_b128 v[160:163], v164 offset:2048
	ds_read_b128 v[164:167], v164 offset:3072
	s_addc_u32 s17, s88, s29
	s_add_u32 s16, s16, 0x6681100
	s_addc_u32 s17, s17, 0
	s_add_u32 s30, s67, s28
	s_addc_u32 s31, s86, s29
	s_cmpk_eq_i32 s28, 0x700
	s_cselect_b32 s35, s9, s17
	s_cselect_b32 s34, s5, s16
	s_cselect_b32 s31, s23, s31
	s_cselect_b32 s30, s21, s30
	v_add_u32_e32 v192, 0xc000, v184
	v_lshl_add_u64 v[194:195], v[134:135], 0, s[28:29]
	v_readfirstlane_b32 s16, v192
	v_add_u32_e32 v192, 0xe000, v184
	s_mov_b32 m0, s16
	v_readfirstlane_b32 s16, v192
	ds_read_b128 v[168:171], v185
	ds_read_b128 v[172:175], v185 offset:1024
	ds_read_b128 v[176:179], v185 offset:2048
	ds_read_b128 v[180:183], v185 offset:3072
	ds_read_b128 v[212:215], v185 offset:4096
	ds_read_b128 v[216:219], v185 offset:5120
	ds_read_b128 v[220:223], v185 offset:6144
	ds_read_b128 v[224:227], v185 offset:7168
	global_load_lds_dwordx4 v[194:195], off
	v_lshl_add_u64 v[194:195], v[132:133], 0, s[28:29]
	s_mov_b32 m0, s16
	s_nop 0
	global_load_lds_dwordx4 v[194:195], off
	s_waitcnt vmcnt(8)
	s_waitcnt lgkmcnt(0)
	s_barrier
	s_setprio 1
	s_waitcnt lgkmcnt(0)
	v_mfma_f32_16x16x32_bf16 v[126:129], v[168:171], v[136:139], v[126:129]
	v_mfma_f32_16x16x32_bf16 v[122:125], v[168:171], v[144:147], v[122:125]
	v_mfma_f32_16x16x32_bf16 v[110:113], v[176:179], v[136:139], v[110:113]
	v_mfma_f32_16x16x32_bf16 v[106:109], v[176:179], v[144:147], v[106:109]
	v_mfma_f32_16x16x32_bf16 v[94:97], v[212:215], v[136:139], v[94:97]
	v_mfma_f32_16x16x32_bf16 v[90:93], v[212:215], v[144:147], v[90:93]
	v_mfma_f32_16x16x32_bf16 v[78:81], v[220:223], v[136:139], v[78:81]
	v_mfma_f32_16x16x32_bf16 v[74:77], v[220:223], v[144:147], v[74:77]
	v_mfma_f32_16x16x32_bf16 v[126:129], v[172:175], v[140:143], v[126:129]
	v_mfma_f32_16x16x32_bf16 v[122:125], v[172:175], v[148:151], v[122:125]
	v_mfma_f32_16x16x32_bf16 v[110:113], v[180:183], v[140:143], v[110:113]
	v_mfma_f32_16x16x32_bf16 v[106:109], v[180:183], v[148:151], v[106:109]
	v_mfma_f32_16x16x32_bf16 v[94:97], v[216:219], v[140:143], v[94:97]
	v_mfma_f32_16x16x32_bf16 v[90:93], v[216:219], v[148:151], v[90:93]
	v_mfma_f32_16x16x32_bf16 v[78:81], v[224:227], v[140:143], v[78:81]
	v_mfma_f32_16x16x32_bf16 v[74:77], v[224:227], v[148:151], v[74:77]
	s_setprio 0
	s_setprio 1
	v_mfma_f32_16x16x32_bf16 v[118:121], v[168:171], v[152:155], v[118:121]
	v_mfma_f32_16x16x32_bf16 v[114:117], v[168:171], v[160:163], v[114:117]
	v_mfma_f32_16x16x32_bf16 v[102:105], v[176:179], v[152:155], v[102:105]
	v_mfma_f32_16x16x32_bf16 v[98:101], v[176:179], v[160:163], v[98:101]
	v_mfma_f32_16x16x32_bf16 v[86:89], v[212:215], v[152:155], v[86:89]
	v_mfma_f32_16x16x32_bf16 v[82:85], v[212:215], v[160:163], v[82:85]
	v_mfma_f32_16x16x32_bf16 v[38:41], v[220:223], v[152:155], v[38:41]
	v_mfma_f32_16x16x32_bf16 v[16:19], v[220:223], v[160:163], v[16:19]
	v_mfma_f32_16x16x32_bf16 v[118:121], v[172:175], v[156:159], v[118:121]
	v_mfma_f32_16x16x32_bf16 v[114:117], v[172:175], v[164:167], v[114:117]
	v_mfma_f32_16x16x32_bf16 v[102:105], v[180:183], v[156:159], v[102:105]
	v_mfma_f32_16x16x32_bf16 v[98:101], v[180:183], v[164:167], v[98:101]
	v_mfma_f32_16x16x32_bf16 v[86:89], v[216:219], v[156:159], v[86:89]
	v_mfma_f32_16x16x32_bf16 v[82:85], v[216:219], v[164:167], v[82:85]
	v_mfma_f32_16x16x32_bf16 v[38:41], v[224:227], v[156:159], v[38:41]
	v_mfma_f32_16x16x32_bf16 v[16:19], v[224:227], v[164:167], v[16:19]
	s_setprio 0
	s_barrier
	v_readfirstlane_b32 s16, v187
	v_lshl_add_u64 v[194:195], s[30:31], 0, v[32:33]
	s_mov_b32 m0, s16
	v_readfirstlane_b32 s16, v188
	ds_read_b128 v[168:171], v185 offset:16384
	ds_read_b128 v[172:175], v185 offset:17408
	ds_read_b128 v[176:179], v185 offset:18432
	ds_read_b128 v[180:183], v185 offset:19456
	ds_read_b128 v[212:215], v185 offset:20480
	ds_read_b128 v[216:219], v185 offset:21504
	ds_read_b128 v[220:223], v185 offset:22528
	ds_read_b128 v[224:227], v185 offset:23552
	global_load_lds_dwordx4 v[194:195], off
	s_mov_b32 m0, s16
	s_add_u32 s16, s30, 0x40000
	v_lshl_add_u64 v[228:229], s[30:31], 0, v[130:131]
	s_addc_u32 s17, s31, 0
	v_readfirstlane_b32 s6, v189
	global_load_lds_dwordx4 v[228:229], off
	v_lshl_add_u64 v[230:231], s[16:17], 0, v[32:33]
	s_mov_b32 m0, s6
	v_readfirstlane_b32 s6, v190
	global_load_lds_dwordx4 v[230:231], off
	v_lshl_add_u64 v[230:231], s[16:17], 0, v[130:131]
	s_mov_b32 m0, s6
	v_readfirstlane_b32 s6, v184
	global_load_lds_dwordx4 v[230:231], off
	v_lshl_add_u64 v[230:231], s[34:35], 0, v[32:33]
	s_mov_b32 m0, s6
	v_readfirstlane_b32 s6, v191
	global_load_lds_dwordx4 v[230:231], off
	v_lshl_add_u64 v[232:233], s[34:35], 0, v[130:131]
	s_mov_b32 m0, s6
	s_nop 0
	global_load_lds_dwordx4 v[232:233], off
	s_waitcnt vmcnt(8)
	s_waitcnt lgkmcnt(0)
	s_barrier
; #define STAGE(bufoff, GB) do { const char* g_ = (GB); \
;         _Pragma("unroll") for (int i_ = 0; i_ < 2; ++i_) __builtin_amdgcn_global_load_lds((const unsigned*)(g_ + voff[i_]), (LAS3 unsigned*)(L + (bufoff) + stoff + i_ * 8192), 16, 0, 0); } while (0)
; #define LDA(dst, b, h) do { _Pragma("unroll") for (int m = 0; m < 4; ++m) _Pragma("unroll") for (int k = 0; k < 2; ++k) dst[m][k] = *(const LAS3 bf16x8*)(L + SA(b, h) + aoff + m * 2048 + k * 1024); } while (0)
; #define LDB(dst, b, h) do { _Pragma("unroll") for (int n = 0; n < 2; ++n) _Pragma("unroll") for (int k = 0; k < 2; ++k) dst[n][k] = *(const LAS3 bf16x8*)(L + SB(b, h) + boff + n * 2048 + k * 1024); } while (0)
; #define WAIT_V(n) asm volatile("s_waitcnt vmcnt(" #n ")" ::: "memory")
; #define WAIT_L(n) asm volatile("s_waitcnt lgkmcnt(" #n ")" ::: "memory")
; #define BAR __builtin_amdgcn_s_barrier()
; #define SCHED __builtin_amdgcn_sched_barrier(0)
; template <int EPI>
; DI void gemm_phase(const bf16_t* __restrict__ A, const bf16_t* __restrict__ Bt, const int K, const int N, const Params& p, const int layer_j, char* lds) {
;     ...
;             WAIT_V(8); WAIT_L(0); BAR; MMA(1, 0, At, B0); MMA(1, 1, At, B1); BAR; SCHED;
;             LDB(B0, 1, 0); LDB(B1, 1, 1); SCHED; LDA(At, 1, 0); STAGE(SA(0, 1), a2 + hstep);
;             WAIT_V(8); WAIT_L(0); BAR; MMA(0, 0, At, B0); MMA(0, 1, At, B1); BAR; SCHED;
;             LDA(At, 1, 1); STAGE(SB(1, 0), b3); STAGE(SB(1, 1), b3 + hstep); STAGE(SA(1, 0), a3);
;             WAIT_V(8); WAIT_L(0); BAR; MMA(1, 0, At, B0); MMA(1, 1, At, B1); BAR; SCHED;
	s_setprio 1
	s_waitcnt lgkmcnt(0)
	v_mfma_f32_16x16x32_bf16 v[70:73], v[168:171], v[136:139], v[70:73]
	v_mfma_f32_16x16x32_bf16 v[54:57], v[168:171], v[144:147], v[54:57]
	v_mfma_f32_16x16x32_bf16 v[66:69], v[176:179], v[136:139], v[66:69]
	v_mfma_f32_16x16x32_bf16 v[50:53], v[176:179], v[144:147], v[50:53]
	v_mfma_f32_16x16x32_bf16 v[62:65], v[212:215], v[136:139], v[62:65]
	v_mfma_f32_16x16x32_bf16 v[46:49], v[212:215], v[144:147], v[46:49]
	v_mfma_f32_16x16x32_bf16 v[58:61], v[220:223], v[136:139], v[58:61]
	v_mfma_f32_16x16x32_bf16 v[42:45], v[220:223], v[144:147], v[42:45]
	v_mfma_f32_16x16x32_bf16 v[70:73], v[172:175], v[140:143], v[70:73]
	v_mfma_f32_16x16x32_bf16 v[54:57], v[172:175], v[148:151], v[54:57]
	v_mfma_f32_16x16x32_bf16 v[66:69], v[180:183], v[140:143], v[66:69]
	v_mfma_f32_16x16x32_bf16 v[50:53], v[180:183], v[148:151], v[50:53]
	v_mfma_f32_16x16x32_bf16 v[62:65], v[216:219], v[140:143], v[62:65]
	v_mfma_f32_16x16x32_bf16 v[46:49], v[216:219], v[148:151], v[46:49]
	v_mfma_f32_16x16x32_bf16 v[58:61], v[224:227], v[140:143], v[58:61]
	v_mfma_f32_16x16x32_bf16 v[42:45], v[224:227], v[148:151], v[42:45]
	s_setprio 0
	s_setprio 1
	v_mfma_f32_16x16x32_bf16 v[34:37], v[168:171], v[152:155], v[34:37]
	v_mfma_f32_16x16x32_bf16 v[12:15], v[168:171], v[160:163], v[12:15]
	v_mfma_f32_16x16x32_bf16 v[28:31], v[176:179], v[152:155], v[28:31]
	v_mfma_f32_16x16x32_bf16 v[8:11], v[176:179], v[160:163], v[8:11]
	v_mfma_f32_16x16x32_bf16 v[24:27], v[212:215], v[152:155], v[24:27]
	v_mfma_f32_16x16x32_bf16 v[4:7], v[212:215], v[160:163], v[4:7]
	v_mfma_f32_16x16x32_bf16 v[20:23], v[220:223], v[152:155], v[20:23]
	v_mfma_f32_16x16x32_bf16 v[0:3], v[220:223], v[160:163], v[0:3]
	v_mfma_f32_16x16x32_bf16 v[34:37], v[172:175], v[156:159], v[34:37]
	v_mfma_f32_16x16x32_bf16 v[12:15], v[172:175], v[164:167], v[12:15]
	v_mfma_f32_16x16x32_bf16 v[28:31], v[180:183], v[156:159], v[28:31]
	v_mfma_f32_16x16x32_bf16 v[8:11], v[180:183], v[164:167], v[8:11]
	v_mfma_f32_16x16x32_bf16 v[24:27], v[216:219], v[156:159], v[24:27]
	v_mfma_f32_16x16x32_bf16 v[4:7], v[216:219], v[164:167], v[4:7]
	v_mfma_f32_16x16x32_bf16 v[20:23], v[224:227], v[156:159], v[20:23]
	v_mfma_f32_16x16x32_bf16 v[0:3], v[224:227], v[164:167], v[0:3]
	s_setprio 0
	s_barrier
	v_add_u32_e32 v148, 0x18000, v186
	v_add_u32_e32 v164, 0x1c000, v186
	ds_read_b128 v[136:139], v148
	ds_read_b128 v[140:143], v148 offset:1024
	ds_read_b128 v[144:147], v148 offset:2048
	ds_read_b128 v[148:151], v148 offset:3072
	ds_read_b128 v[152:155], v164
	ds_read_b128 v[156:159], v164 offset:1024
	ds_read_b128 v[160:163], v164 offset:2048
	ds_read_b128 v[164:167], v164 offset:3072
	s_add_u32 s16, s34, 0x40000
	s_addc_u32 s17, s35, 0
	v_readfirstlane_b32 s6, v204
	v_lshl_add_u64 v[234:235], s[16:17], 0, v[32:33]
	s_mov_b32 m0, s6
	v_readfirstlane_b32 s6, v205
	ds_read_b128 v[168:171], v185 offset:32768
	ds_read_b128 v[172:175], v185 offset:33792
	ds_read_b128 v[176:179], v185 offset:34816
	ds_read_b128 v[180:183], v185 offset:35840
	ds_read_b128 v[212:215], v185 offset:36864
	ds_read_b128 v[216:219], v185 offset:37888
	ds_read_b128 v[220:223], v185 offset:38912
	ds_read_b128 v[224:227], v185 offset:39936
	global_load_lds_dwordx4 v[234:235], off
	v_lshl_add_u64 v[234:235], s[16:17], 0, v[130:131]
	s_mov_b32 m0, s6
	s_nop 0
	global_load_lds_dwordx4 v[234:235], off
	s_waitcnt vmcnt(8)
	s_waitcnt lgkmcnt(0)
	s_barrier
	s_setprio 1
	s_waitcnt lgkmcnt(0)
	v_mfma_f32_16x16x32_bf16 v[126:129], v[168:171], v[136:139], v[126:129]
	v_mfma_f32_16x16x32_bf16 v[122:125], v[168:171], v[144:147], v[122:125]
	v_mfma_f32_16x16x32_bf16 v[110:113], v[176:179], v[136:139], v[110:113]
	v_mfma_f32_16x16x32_bf16 v[106:109], v[176:179], v[144:147], v[106:109]
	v_mfma_f32_16x16x32_bf16 v[94:97], v[212:215], v[136:139], v[94:97]
	v_mfma_f32_16x16x32_bf16 v[90:93], v[212:215], v[144:147], v[90:93]
	v_mfma_f32_16x16x32_bf16 v[78:81], v[220:223], v[136:139], v[78:81]
	v_mfma_f32_16x16x32_bf16 v[74:77], v[220:223], v[144:147], v[74:77]
	v_mfma_f32_16x16x32_bf16 v[126:129], v[172:175], v[140:143], v[126:129]
	v_mfma_f32_16x16x32_bf16 v[122:125], v[172:175], v[148:151], v[122:125]
	v_mfma_f32_16x16x32_bf16 v[110:113], v[180:183], v[140:143], v[110:113]
	v_mfma_f32_16x16x32_bf16 v[106:109], v[180:183], v[148:151], v[106:109]
	v_mfma_f32_16x16x32_bf16 v[94:97], v[216:219], v[140:143], v[94:97]
	v_mfma_f32_16x16x32_bf16 v[90:93], v[216:219], v[148:151], v[90:93]
	v_mfma_f32_16x16x32_bf16 v[78:81], v[224:227], v[140:143], v[78:81]
	v_mfma_f32_16x16x32_bf16 v[74:77], v[224:227], v[148:151], v[74:77]
	s_setprio 0
	s_setprio 1
	v_mfma_f32_16x16x32_bf16 v[118:121], v[168:171], v[152:155], v[118:121]
	v_mfma_f32_16x16x32_bf16 v[114:117], v[168:171], v[160:163], v[114:117]
	v_mfma_f32_16x16x32_bf16 v[102:105], v[176:179], v[152:155], v[102:105]
	v_mfma_f32_16x16x32_bf16 v[98:101], v[176:179], v[160:163], v[98:101]
	v_mfma_f32_16x16x32_bf16 v[86:89], v[212:215], v[152:155], v[86:89]
	v_mfma_f32_16x16x32_bf16 v[82:85], v[212:215], v[160:163], v[82:85]
	v_mfma_f32_16x16x32_bf16 v[38:41], v[220:223], v[152:155], v[38:41]
	v_mfma_f32_16x16x32_bf16 v[16:19], v[220:223], v[160:163], v[16:19]
	v_mfma_f32_16x16x32_bf16 v[118:121], v[172:175], v[156:159], v[118:121]
	v_mfma_f32_16x16x32_bf16 v[114:117], v[172:175], v[164:167], v[114:117]
	v_mfma_f32_16x16x32_bf16 v[102:105], v[180:183], v[156:159], v[102:105]
	v_mfma_f32_16x16x32_bf16 v[98:101], v[180:183], v[164:167], v[98:101]
	v_mfma_f32_16x16x32_bf16 v[86:89], v[216:219], v[156:159], v[86:89]
	v_mfma_f32_16x16x32_bf16 v[82:85], v[216:219], v[164:167], v[82:85]
	v_mfma_f32_16x16x32_bf16 v[38:41], v[224:227], v[156:159], v[38:41]
	v_mfma_f32_16x16x32_bf16 v[16:19], v[224:227], v[164:167], v[16:19]
	s_setprio 0
	s_barrier
; #define STAGE(bufoff, GB) do { const char* g_ = (GB); \
;         _Pragma("unroll") for (int i_ = 0; i_ < 2; ++i_) __builtin_amdgcn_global_load_lds((const unsigned*)(g_ + voff[i_]), (LAS3 unsigned*)(L + (bufoff) + stoff + i_ * 8192), 16, 0, 0); } while (0)
; #define LDA(dst, b, h) do { _Pragma("unroll") for (int m = 0; m < 4; ++m) _Pragma("unroll") for (int k = 0; k < 2; ++k) dst[m][k] = *(const LAS3 bf16x8*)(L + SA(b, h) + aoff + m * 2048 + k * 1024); } while (0)
; #define WAIT_V(n) asm volatile("s_waitcnt vmcnt(" #n ")" ::: "memory")
; #define WAIT_L(n) asm volatile("s_waitcnt lgkmcnt(" #n ")" ::: "memory")
; #define BAR __builtin_amdgcn_s_barrier()
; #define SCHED __builtin_amdgcn_sched_barrier(0)
; template <int EPI>
; DI void gemm_phase(const bf16_t* __restrict__ A, const bf16_t* __restrict__ Bt, const int K, const int N, const Params& p, const int layer_j, char* lds) {
;     ...
;             LDA(At, 1, 1); STAGE(SB(1, 0), b3); STAGE(SB(1, 1), b3 + hstep); STAGE(SA(1, 0), a3);
;             WAIT_V(8); WAIT_L(0); BAR; MMA(1, 0, At, B0); MMA(1, 1, At, B1); BAR; SCHED;
;         }
	v_readfirstlane_b32 s6, v206
	v_lshl_add_u64 v[194:195], v[194:195], 0, s[94:95]
	s_mov_b32 m0, s6
	v_readfirstlane_b32 s6, v207
	s_add_u32 s16, s30, 0x40080
	ds_read_b128 v[168:171], v185 offset:49152
	ds_read_b128 v[172:175], v185 offset:50176
	ds_read_b128 v[176:179], v185 offset:51200
	ds_read_b128 v[180:183], v185 offset:52224
	ds_read_b128 v[212:215], v185 offset:53248
	ds_read_b128 v[216:219], v185 offset:54272
	ds_read_b128 v[220:223], v185 offset:55296
	ds_read_b128 v[224:227], v185 offset:56320
	global_load_lds_dwordx4 v[194:195], off
	v_lshl_add_u64 v[194:195], v[228:229], 0, s[94:95]
	s_mov_b32 m0, s6
	s_addc_u32 s17, s31, 0
	v_readfirstlane_b32 s6, v210
	global_load_lds_dwordx4 v[194:195], off
	v_lshl_add_u64 v[194:195], s[16:17], 0, v[32:33]
	s_mov_b32 m0, s6
	v_readfirstlane_b32 s6, v211
	global_load_lds_dwordx4 v[194:195], off
	v_lshl_add_u64 v[194:195], s[16:17], 0, v[130:131]
	s_mov_b32 m0, s6
	v_readfirstlane_b32 s6, v208
	global_load_lds_dwordx4 v[194:195], off
	v_lshl_add_u64 v[194:195], v[230:231], 0, s[94:95]
	s_mov_b32 m0, s6
	v_readfirstlane_b32 s6, v209
	global_load_lds_dwordx4 v[194:195], off
	v_lshl_add_u64 v[194:195], v[232:233], 0, s[94:95]
	s_mov_b32 m0, s6
	s_nop 0
	global_load_lds_dwordx4 v[194:195], off
	s_waitcnt vmcnt(8)
	s_waitcnt lgkmcnt(0)
	s_barrier
	s_setprio 1
	s_waitcnt lgkmcnt(0)
	v_mfma_f32_16x16x32_bf16 v[70:73], v[168:171], v[136:139], v[70:73]
	v_mfma_f32_16x16x32_bf16 v[54:57], v[168:171], v[144:147], v[54:57]
	v_mfma_f32_16x16x32_bf16 v[66:69], v[176:179], v[136:139], v[66:69]
	v_mfma_f32_16x16x32_bf16 v[50:53], v[176:179], v[144:147], v[50:53]
	v_mfma_f32_16x16x32_bf16 v[62:65], v[212:215], v[136:139], v[62:65]
	v_mfma_f32_16x16x32_bf16 v[46:49], v[212:215], v[144:147], v[46:49]
	v_mfma_f32_16x16x32_bf16 v[58:61], v[220:223], v[136:139], v[58:61]
	v_mfma_f32_16x16x32_bf16 v[42:45], v[220:223], v[144:147], v[42:45]
	v_mfma_f32_16x16x32_bf16 v[70:73], v[172:175], v[140:143], v[70:73]
	v_mfma_f32_16x16x32_bf16 v[54:57], v[172:175], v[148:151], v[54:57]
	v_mfma_f32_16x16x32_bf16 v[66:69], v[180:183], v[140:143], v[66:69]
	v_mfma_f32_16x16x32_bf16 v[50:53], v[180:183], v[148:151], v[50:53]
	v_mfma_f32_16x16x32_bf16 v[62:65], v[216:219], v[140:143], v[62:65]
	v_mfma_f32_16x16x32_bf16 v[46:49], v[216:219], v[148:151], v[46:49]
	v_mfma_f32_16x16x32_bf16 v[58:61], v[224:227], v[140:143], v[58:61]
	v_mfma_f32_16x16x32_bf16 v[42:45], v[224:227], v[148:151], v[42:45]
	s_setprio 0
	s_setprio 1
	v_mfma_f32_16x16x32_bf16 v[34:37], v[168:171], v[152:155], v[34:37]
	v_mfma_f32_16x16x32_bf16 v[12:15], v[168:171], v[160:163], v[12:15]
	v_mfma_f32_16x16x32_bf16 v[28:31], v[176:179], v[152:155], v[28:31]
	v_mfma_f32_16x16x32_bf16 v[8:11], v[176:179], v[160:163], v[8:11]
	v_mfma_f32_16x16x32_bf16 v[24:27], v[212:215], v[152:155], v[24:27]
	v_mfma_f32_16x16x32_bf16 v[4:7], v[212:215], v[160:163], v[4:7]
	v_mfma_f32_16x16x32_bf16 v[20:23], v[220:223], v[152:155], v[20:23]
	v_mfma_f32_16x16x32_bf16 v[0:3], v[220:223], v[160:163], v[0:3]
	v_mfma_f32_16x16x32_bf16 v[34:37], v[172:175], v[156:159], v[34:37]
	v_mfma_f32_16x16x32_bf16 v[12:15], v[172:175], v[164:167], v[12:15]
	v_mfma_f32_16x16x32_bf16 v[28:31], v[180:183], v[156:159], v[28:31]
	v_mfma_f32_16x16x32_bf16 v[8:11], v[180:183], v[164:167], v[8:11]
	v_mfma_f32_16x16x32_bf16 v[24:27], v[216:219], v[156:159], v[24:27]
	v_mfma_f32_16x16x32_bf16 v[4:7], v[216:219], v[164:167], v[4:7]
	v_mfma_f32_16x16x32_bf16 v[20:23], v[224:227], v[156:159], v[20:23]
	v_mfma_f32_16x16x32_bf16 v[0:3], v[224:227], v[164:167], v[0:3]
	s_setprio 0
	s_barrier
	s_add_i32 vcc_lo, vcc_lo, 2
	s_add_u32 s28, s28, 0x100
	s_addc_u32 s29, s29, 0
	s_cmp_gt_u32 vcc_lo, 13
	s_cbranch_scc0 .LBB0_338
	v_readlane_b32 s6, v254, 12
	v_readlane_b32 s7, v254, 13
	s_and_b64 vcc, exec, s[6:7]
	s_cbranch_vccz .LBB0_341
	s_barrier

; #define STAGE(bufoff, GB) do { const char* g_ = (GB); \
;         _Pragma("unroll") for (int i_ = 0; i_ < 2; ++i_) __builtin_amdgcn_global_load_lds((const unsigned*)(g_ + voff[i_]), (LAS3 unsigned*)(L + (bufoff) + stoff + i_ * 8192), 16, 0, 0); } while (0)
; #define LDA(dst, b, h) do { _Pragma("unroll") for (int m = 0; m < 4; ++m) _Pragma("unroll") for (int k = 0; k < 2; ++k) dst[m][k] = *(const LAS3 bf16x8*)(L + SA(b, h) + aoff + m * 2048 + k * 1024); } while (0)
; #define LDB(dst, b, h) do { _Pragma("unroll") for (int n = 0; n < 2; ++n) _Pragma("unroll") for (int k = 0; k < 2; ++k) dst[n][k] = *(const LAS3 bf16x8*)(L + SB(b, h) + boff + n * 2048 + k * 1024); } while (0)
; #define WAIT_V(n) asm volatile("s_waitcnt vmcnt(" #n ")" ::: "memory")
; #define WAIT_L(n) asm volatile("s_waitcnt lgkmcnt(" #n ")" ::: "memory")
; #define BAR __builtin_amdgcn_s_barrier()
; #define SCHED __builtin_amdgcn_sched_barrier(0)
; template <int EPI>
; DI void gemm_phase(const bf16_t* __restrict__ A, const bf16_t* __restrict__ Bt, const int K, const int N, const Params& p, const int layer_j, char* lds) {
;     ...
;         for (int t = 0; t < nt; t += 2) {
;             const bool last = (t == nt - 2);
;             const char* a1 = cA + (size_t)(t + 1) * kstep;
;             const char* a2 = last ? nA : cA + (size_t)(t + 2) * kstep; const char* b2 = last ? nB : cB + (size_t)(t + 2) * kstep;
;             const char* a3 = a2 + kstep; const char* b3 = b2 + kstep;
;             LDB(B0, 0, 0); LDB(B1, 0, 1); SCHED; LDA(At, 0, 0); STAGE(SA(1, 1), a1 + hstep);
;             WAIT_V(8); WAIT_L(0); BAR; MMA(0, 0, At, B0); MMA(0, 1, At, B1); BAR; SCHED;
;             LDA(At, 0, 1); STAGE(SB(0, 0), b2); STAGE(SB(0, 1), b2 + hstep); STAGE(SA(0, 0), a2);
;             WAIT_V(8); WAIT_L(0); BAR; MMA(1, 0, At, B0); MMA(1, 1, At, B1); BAR; SCHED;
.LBB0_374:
	v_add_u32_e32 v136, 0x10000, v140
	ds_read_b128 v[154:157], v136
	ds_read_b128 v[158:161], v136 offset:1024
	ds_read_b128 v[162:165], v136 offset:2048
	ds_read_b128 v[166:169], v136 offset:3072
	v_add_u32_e32 v136, 0x14000, v140
	s_add_u32 s28, s67, s26
	ds_read_b128 v[170:173], v136
	ds_read_b128 v[174:177], v136 offset:1024
	ds_read_b128 v[178:181], v136 offset:2048
	ds_read_b128 v[182:185], v136 offset:3072
	s_addc_u32 s29, s86, s27
	s_add_u32 s28, s28, 0x6681100
	s_addc_u32 s29, s29, 0
	s_add_u32 s88, s65, s26
	s_addc_u32 vcc_lo, s66, s27
	s_cmpk_eq_i32 s26, 0x700
	s_cselect_b32 s31, s15, s29
	s_cselect_b32 s30, s13, s28
	s_cselect_b32 s29, s64, vcc_lo
	s_cselect_b32 s28, s23, s88
	v_add_u32_e32 v190, 0xc000, v138
	v_lshl_add_u64 v[136:137], v[134:135], 0, s[26:27]
	v_readfirstlane_b32 s88, v190
	v_add_u32_e32 v190, 0xe000, v138
	s_mov_b32 m0, s88
	v_readfirstlane_b32 s88, v190
	ds_read_b128 v[186:189], v139
	ds_read_b128 v[204:207], v139 offset:1024
	ds_read_b128 v[208:211], v139 offset:2048
	ds_read_b128 v[212:215], v139 offset:3072
	ds_read_b128 v[216:219], v139 offset:4096
	ds_read_b128 v[220:223], v139 offset:5120
	ds_read_b128 v[224:227], v139 offset:6144
	ds_read_b128 v[228:231], v139 offset:7168
	global_load_lds_dwordx4 v[136:137], off
	v_lshl_add_u64 v[136:137], v[132:133], 0, s[26:27]
	s_mov_b32 m0, s88
	s_nop 0
	global_load_lds_dwordx4 v[136:137], off
	s_waitcnt vmcnt(8)
	s_waitcnt lgkmcnt(0)
	s_barrier
	s_setprio 1
	s_waitcnt lgkmcnt(0)
	v_mfma_f32_16x16x32_bf16 v[126:129], v[186:189], v[154:157], v[126:129]
	v_mfma_f32_16x16x32_bf16 v[110:113], v[186:189], v[162:165], v[110:113]
	v_mfma_f32_16x16x32_bf16 v[122:125], v[208:211], v[154:157], v[122:125]
	v_mfma_f32_16x16x32_bf16 v[106:109], v[208:211], v[162:165], v[106:109]
	v_mfma_f32_16x16x32_bf16 v[118:121], v[216:219], v[154:157], v[118:121]
	v_mfma_f32_16x16x32_bf16 v[102:105], v[216:219], v[162:165], v[102:105]
	v_mfma_f32_16x16x32_bf16 v[114:117], v[224:227], v[154:157], v[114:117]
	v_mfma_f32_16x16x32_bf16 v[94:97], v[224:227], v[162:165], v[94:97]
	v_mfma_f32_16x16x32_bf16 v[126:129], v[204:207], v[158:161], v[126:129]
	v_mfma_f32_16x16x32_bf16 v[110:113], v[204:207], v[166:169], v[110:113]
	v_mfma_f32_16x16x32_bf16 v[122:125], v[212:215], v[158:161], v[122:125]
	v_mfma_f32_16x16x32_bf16 v[106:109], v[212:215], v[166:169], v[106:109]
	v_mfma_f32_16x16x32_bf16 v[118:121], v[220:223], v[158:161], v[118:121]
	v_mfma_f32_16x16x32_bf16 v[102:105], v[220:223], v[166:169], v[102:105]
	v_mfma_f32_16x16x32_bf16 v[114:117], v[228:231], v[158:161], v[114:117]
	v_mfma_f32_16x16x32_bf16 v[94:97], v[228:231], v[166:169], v[94:97]
	s_setprio 0
	s_setprio 1
	v_mfma_f32_16x16x32_bf16 v[74:77], v[186:189], v[170:173], v[74:77]
	v_mfma_f32_16x16x32_bf16 v[34:37], v[186:189], v[178:181], v[34:37]
	v_mfma_f32_16x16x32_bf16 v[62:65], v[208:211], v[170:173], v[62:65]
	v_mfma_f32_16x16x32_bf16 v[24:27], v[208:211], v[178:181], v[24:27]
	v_mfma_f32_16x16x32_bf16 v[54:57], v[216:219], v[170:173], v[54:57]
	v_mfma_f32_16x16x32_bf16 v[20:23], v[216:219], v[178:181], v[20:23]
	v_mfma_f32_16x16x32_bf16 v[38:41], v[224:227], v[170:173], v[38:41]
	v_mfma_f32_16x16x32_bf16 v[12:15], v[224:227], v[178:181], v[12:15]
	v_mfma_f32_16x16x32_bf16 v[74:77], v[204:207], v[174:177], v[74:77]
	v_mfma_f32_16x16x32_bf16 v[34:37], v[204:207], v[182:185], v[34:37]
	v_mfma_f32_16x16x32_bf16 v[62:65], v[212:215], v[174:177], v[62:65]
	v_mfma_f32_16x16x32_bf16 v[24:27], v[212:215], v[182:185], v[24:27]
	v_mfma_f32_16x16x32_bf16 v[54:57], v[220:223], v[174:177], v[54:57]
	v_mfma_f32_16x16x32_bf16 v[20:23], v[220:223], v[182:185], v[20:23]
	v_mfma_f32_16x16x32_bf16 v[38:41], v[228:231], v[174:177], v[38:41]
	v_mfma_f32_16x16x32_bf16 v[12:15], v[228:231], v[182:185], v[12:15]
	s_setprio 0
	s_barrier
	v_readfirstlane_b32 s88, v141
	v_lshl_add_u64 v[136:137], s[28:29], 0, v[32:33]
	s_mov_b32 m0, s88
	v_readfirstlane_b32 s88, v142
	s_add_u32 vcc_lo, s28, 0x40000
	ds_read_b128 v[186:189], v139 offset:16384
	ds_read_b128 v[204:207], v139 offset:17408
	ds_read_b128 v[208:211], v139 offset:18432
	ds_read_b128 v[212:215], v139 offset:19456
	ds_read_b128 v[216:219], v139 offset:20480
	ds_read_b128 v[220:223], v139 offset:21504
	ds_read_b128 v[224:227], v139 offset:22528
	ds_read_b128 v[228:231], v139 offset:23552
	global_load_lds_dwordx4 v[136:137], off
	v_lshl_add_u64 v[190:191], s[28:29], 0, v[130:131]
	s_mov_b32 m0, s88
	s_addc_u32 vcc_hi, s29, 0
	v_readfirstlane_b32 s88, v143
	global_load_lds_dwordx4 v[190:191], off
	v_lshl_add_u64 v[194:195], vcc, 0, v[32:33]
	s_mov_b32 m0, s88
	v_readfirstlane_b32 s88, v144
	global_load_lds_dwordx4 v[194:195], off
	v_lshl_add_u64 v[194:195], vcc, 0, v[130:131]
	s_mov_b32 m0, s88
	v_readfirstlane_b32 s88, v138
	global_load_lds_dwordx4 v[194:195], off
	v_lshl_add_u64 v[194:195], s[30:31], 0, v[32:33]
	s_mov_b32 m0, s88
	v_readfirstlane_b32 s88, v145
	global_load_lds_dwordx4 v[194:195], off
	v_lshl_add_u64 v[232:233], s[30:31], 0, v[130:131]
	s_mov_b32 m0, s88
	s_nop 0
	global_load_lds_dwordx4 v[232:233], off
	s_waitcnt vmcnt(8)
	s_waitcnt lgkmcnt(0)
	s_barrier
; #define STAGE(bufoff, GB) do { const char* g_ = (GB); \
;         _Pragma("unroll") for (int i_ = 0; i_ < 2; ++i_) __builtin_amdgcn_global_load_lds((const unsigned*)(g_ + voff[i_]), (LAS3 unsigned*)(L + (bufoff) + stoff + i_ * 8192), 16, 0, 0); } while (0)
; #define LDA(dst, b, h) do { _Pragma("unroll") for (int m = 0; m < 4; ++m) _Pragma("unroll") for (int k = 0; k < 2; ++k) dst[m][k] = *(const LAS3 bf16x8*)(L + SA(b, h) + aoff + m * 2048 + k * 1024); } while (0)
; #define LDB(dst, b, h) do { _Pragma("unroll") for (int n = 0; n < 2; ++n) _Pragma("unroll") for (int k = 0; k < 2; ++k) dst[n][k] = *(const LAS3 bf16x8*)(L + SB(b, h) + boff + n * 2048 + k * 1024); } while (0)
; #define WAIT_V(n) asm volatile("s_waitcnt vmcnt(" #n ")" ::: "memory")
; #define WAIT_L(n) asm volatile("s_waitcnt lgkmcnt(" #n ")" ::: "memory")
; #define BAR __builtin_amdgcn_s_barrier()
; #define SCHED __builtin_amdgcn_sched_barrier(0)
; template <int EPI>
; DI void gemm_phase(const bf16_t* __restrict__ A, const bf16_t* __restrict__ Bt, const int K, const int N, const Params& p, const int layer_j, char* lds) {
;     ...
;             WAIT_V(8); WAIT_L(0); BAR; MMA(1, 0, At, B0); MMA(1, 1, At, B1); BAR; SCHED;
;             LDB(B0, 1, 0); LDB(B1, 1, 1); SCHED; LDA(At, 1, 0); STAGE(SA(0, 1), a2 + hstep);
;             WAIT_V(8); WAIT_L(0); BAR; MMA(0, 0, At, B0); MMA(0, 1, At, B1); BAR; SCHED;
;             LDA(At, 1, 1); STAGE(SB(1, 0), b3); STAGE(SB(1, 1), b3 + hstep); STAGE(SA(1, 0), a3);
;             WAIT_V(8); WAIT_L(0); BAR; MMA(1, 0, At, B0); MMA(1, 1, At, B1); BAR; SCHED;
	s_setprio 1
	s_waitcnt lgkmcnt(0)
	v_mfma_f32_16x16x32_bf16 v[98:101], v[186:189], v[154:157], v[98:101]
	v_mfma_f32_16x16x32_bf16 v[66:69], v[186:189], v[162:165], v[66:69]
	v_mfma_f32_16x16x32_bf16 v[90:93], v[208:211], v[154:157], v[90:93]
	v_mfma_f32_16x16x32_bf16 v[58:61], v[208:211], v[162:165], v[58:61]
	v_mfma_f32_16x16x32_bf16 v[86:89], v[216:219], v[154:157], v[86:89]
	v_mfma_f32_16x16x32_bf16 v[42:45], v[216:219], v[162:165], v[42:45]
	v_mfma_f32_16x16x32_bf16 v[70:73], v[224:227], v[154:157], v[70:73]
	v_mfma_f32_16x16x32_bf16 v[28:31], v[224:227], v[162:165], v[28:31]
	v_mfma_f32_16x16x32_bf16 v[98:101], v[204:207], v[158:161], v[98:101]
	v_mfma_f32_16x16x32_bf16 v[66:69], v[204:207], v[166:169], v[66:69]
	v_mfma_f32_16x16x32_bf16 v[90:93], v[212:215], v[158:161], v[90:93]
	v_mfma_f32_16x16x32_bf16 v[58:61], v[212:215], v[166:169], v[58:61]
	v_mfma_f32_16x16x32_bf16 v[86:89], v[220:223], v[158:161], v[86:89]
	v_mfma_f32_16x16x32_bf16 v[42:45], v[220:223], v[166:169], v[42:45]
	v_mfma_f32_16x16x32_bf16 v[70:73], v[228:231], v[158:161], v[70:73]
	v_mfma_f32_16x16x32_bf16 v[28:31], v[228:231], v[166:169], v[28:31]
	s_setprio 0
	s_setprio 1
	v_mfma_f32_16x16x32_bf16 v[16:19], v[186:189], v[170:173], v[16:19]
	v_mfma_f32_16x16x32_bf16 v[4:7], v[186:189], v[178:181], v[4:7]
	v_mfma_f32_16x16x32_bf16 v[8:11], v[208:211], v[170:173], v[8:11]
	v_mfma_f32_16x16x32_bf16 v[0:3], v[208:211], v[178:181], v[0:3]
	v_mfma_f32_16x16x32_bf16 v[78:81], v[216:219], v[170:173], v[78:81]
	v_mfma_f32_16x16x32_bf16 v[46:49], v[216:219], v[178:181], v[46:49]
	v_mfma_f32_16x16x32_bf16 v[82:85], v[224:227], v[170:173], v[82:85]
	v_mfma_f32_16x16x32_bf16 v[50:53], v[224:227], v[178:181], v[50:53]
	v_mfma_f32_16x16x32_bf16 v[16:19], v[204:207], v[174:177], v[16:19]
	v_mfma_f32_16x16x32_bf16 v[4:7], v[204:207], v[182:185], v[4:7]
	v_mfma_f32_16x16x32_bf16 v[8:11], v[212:215], v[174:177], v[8:11]
	v_mfma_f32_16x16x32_bf16 v[0:3], v[212:215], v[182:185], v[0:3]
	v_mfma_f32_16x16x32_bf16 v[78:81], v[220:223], v[174:177], v[78:81]
	v_mfma_f32_16x16x32_bf16 v[46:49], v[220:223], v[182:185], v[46:49]
	v_mfma_f32_16x16x32_bf16 v[82:85], v[228:231], v[174:177], v[82:85]
	v_mfma_f32_16x16x32_bf16 v[50:53], v[228:231], v[182:185], v[50:53]
	s_setprio 0
	s_barrier
	v_add_u32_e32 v166, 0x18000, v140
	v_add_u32_e32 v182, 0x1c000, v140
	ds_read_b128 v[154:157], v166
	ds_read_b128 v[158:161], v166 offset:1024
	ds_read_b128 v[162:165], v166 offset:2048
	ds_read_b128 v[166:169], v166 offset:3072
	ds_read_b128 v[170:173], v182
	ds_read_b128 v[174:177], v182 offset:1024
	ds_read_b128 v[178:181], v182 offset:2048
	ds_read_b128 v[182:185], v182 offset:3072
	s_add_u32 s30, s30, 0x40000
	s_addc_u32 s31, s31, 0
	v_readfirstlane_b32 s88, v146
	v_lshl_add_u64 v[234:235], s[30:31], 0, v[32:33]
	s_mov_b32 m0, s88
	ds_read_b128 v[186:189], v139 offset:32768
	ds_read_b128 v[204:207], v139 offset:33792
	ds_read_b128 v[208:211], v139 offset:34816
	ds_read_b128 v[212:215], v139 offset:35840
	ds_read_b128 v[216:219], v139 offset:36864
	ds_read_b128 v[220:223], v139 offset:37888
	ds_read_b128 v[224:227], v139 offset:38912
	ds_read_b128 v[228:231], v139 offset:39936
	global_load_lds_dwordx4 v[234:235], off
	v_lshl_add_u64 v[234:235], s[30:31], 0, v[130:131]
	v_readfirstlane_b32 s30, v147
	s_mov_b32 m0, s30
	s_nop 0
	global_load_lds_dwordx4 v[234:235], off
	s_waitcnt vmcnt(8)
	s_waitcnt lgkmcnt(0)
	s_barrier
	s_setprio 1
	s_waitcnt lgkmcnt(0)
	v_mfma_f32_16x16x32_bf16 v[126:129], v[186:189], v[154:157], v[126:129]
	v_mfma_f32_16x16x32_bf16 v[110:113], v[186:189], v[162:165], v[110:113]
	v_mfma_f32_16x16x32_bf16 v[122:125], v[208:211], v[154:157], v[122:125]
	v_mfma_f32_16x16x32_bf16 v[106:109], v[208:211], v[162:165], v[106:109]
	v_mfma_f32_16x16x32_bf16 v[118:121], v[216:219], v[154:157], v[118:121]
	v_mfma_f32_16x16x32_bf16 v[102:105], v[216:219], v[162:165], v[102:105]
	v_mfma_f32_16x16x32_bf16 v[114:117], v[224:227], v[154:157], v[114:117]
	v_mfma_f32_16x16x32_bf16 v[94:97], v[224:227], v[162:165], v[94:97]
	v_mfma_f32_16x16x32_bf16 v[126:129], v[204:207], v[158:161], v[126:129]
	v_mfma_f32_16x16x32_bf16 v[110:113], v[204:207], v[166:169], v[110:113]
	v_mfma_f32_16x16x32_bf16 v[122:125], v[212:215], v[158:161], v[122:125]
	v_mfma_f32_16x16x32_bf16 v[106:109], v[212:215], v[166:169], v[106:109]
	v_mfma_f32_16x16x32_bf16 v[118:121], v[220:223], v[158:161], v[118:121]
	v_mfma_f32_16x16x32_bf16 v[102:105], v[220:223], v[166:169], v[102:105]
	v_mfma_f32_16x16x32_bf16 v[114:117], v[228:231], v[158:161], v[114:117]
	v_mfma_f32_16x16x32_bf16 v[94:97], v[228:231], v[166:169], v[94:97]
	s_setprio 0
	s_setprio 1
	v_mfma_f32_16x16x32_bf16 v[74:77], v[186:189], v[170:173], v[74:77]
	v_mfma_f32_16x16x32_bf16 v[34:37], v[186:189], v[178:181], v[34:37]
	v_mfma_f32_16x16x32_bf16 v[62:65], v[208:211], v[170:173], v[62:65]
	v_mfma_f32_16x16x32_bf16 v[24:27], v[208:211], v[178:181], v[24:27]
	v_mfma_f32_16x16x32_bf16 v[54:57], v[216:219], v[170:173], v[54:57]
	v_mfma_f32_16x16x32_bf16 v[20:23], v[216:219], v[178:181], v[20:23]
	v_mfma_f32_16x16x32_bf16 v[38:41], v[224:227], v[170:173], v[38:41]
	v_mfma_f32_16x16x32_bf16 v[12:15], v[224:227], v[178:181], v[12:15]
	v_mfma_f32_16x16x32_bf16 v[74:77], v[204:207], v[174:177], v[74:77]
	v_mfma_f32_16x16x32_bf16 v[34:37], v[204:207], v[182:185], v[34:37]
	v_mfma_f32_16x16x32_bf16 v[62:65], v[212:215], v[174:177], v[62:65]
	v_mfma_f32_16x16x32_bf16 v[24:27], v[212:215], v[182:185], v[24:27]
	v_mfma_f32_16x16x32_bf16 v[54:57], v[220:223], v[174:177], v[54:57]
	v_mfma_f32_16x16x32_bf16 v[20:23], v[220:223], v[182:185], v[20:23]
	v_mfma_f32_16x16x32_bf16 v[38:41], v[228:231], v[174:177], v[38:41]
	v_mfma_f32_16x16x32_bf16 v[12:15], v[228:231], v[182:185], v[12:15]
	s_setprio 0
	s_barrier
; #define STAGE(bufoff, GB) do { const char* g_ = (GB); \
;         _Pragma("unroll") for (int i_ = 0; i_ < 2; ++i_) __builtin_amdgcn_global_load_lds((const unsigned*)(g_ + voff[i_]), (LAS3 unsigned*)(L + (bufoff) + stoff + i_ * 8192), 16, 0, 0); } while (0)
; #define LDA(dst, b, h) do { _Pragma("unroll") for (int m = 0; m < 4; ++m) _Pragma("unroll") for (int k = 0; k < 2; ++k) dst[m][k] = *(const LAS3 bf16x8*)(L + SA(b, h) + aoff + m * 2048 + k * 1024); } while (0)
; #define WAIT_V(n) asm volatile("s_waitcnt vmcnt(" #n ")" ::: "memory")
; #define WAIT_L(n) asm volatile("s_waitcnt lgkmcnt(" #n ")" ::: "memory")
; #define BAR __builtin_amdgcn_s_barrier()
; #define SCHED __builtin_amdgcn_sched_barrier(0)
; template <int EPI>
; DI void gemm_phase(const bf16_t* __restrict__ A, const bf16_t* __restrict__ Bt, const int K, const int N, const Params& p, const int layer_j, char* lds) {
;     ...
;             LDA(At, 1, 1); STAGE(SB(1, 0), b3); STAGE(SB(1, 1), b3 + hstep); STAGE(SA(1, 0), a3);
;             WAIT_V(8); WAIT_L(0); BAR; MMA(1, 0, At, B0); MMA(1, 1, At, B1); BAR; SCHED;
;         }
	v_readfirstlane_b32 s30, v148
	v_lshl_add_u64 v[136:137], v[136:137], 0, s[94:95]
	s_mov_b32 m0, s30
	v_readfirstlane_b32 s30, v149
	s_add_u32 s28, s28, 0x40080
	ds_read_b128 v[186:189], v139 offset:49152
	ds_read_b128 v[204:207], v139 offset:50176
	ds_read_b128 v[208:211], v139 offset:51200
	ds_read_b128 v[212:215], v139 offset:52224
	ds_read_b128 v[216:219], v139 offset:53248
	ds_read_b128 v[220:223], v139 offset:54272
	ds_read_b128 v[224:227], v139 offset:55296
	ds_read_b128 v[228:231], v139 offset:56320
	global_load_lds_dwordx4 v[136:137], off
	v_lshl_add_u64 v[136:137], v[190:191], 0, s[94:95]
	s_mov_b32 m0, s30
	s_addc_u32 s29, s29, 0
	v_readfirstlane_b32 s30, v152
	global_load_lds_dwordx4 v[136:137], off
	v_lshl_add_u64 v[136:137], s[28:29], 0, v[32:33]
	s_mov_b32 m0, s30
	s_nop 0
	global_load_lds_dwordx4 v[136:137], off
	v_lshl_add_u64 v[136:137], s[28:29], 0, v[130:131]
	v_readfirstlane_b32 s28, v153
	s_mov_b32 m0, s28
	v_readfirstlane_b32 s28, v150
	global_load_lds_dwordx4 v[136:137], off
	v_lshl_add_u64 v[136:137], v[194:195], 0, s[94:95]
	s_mov_b32 m0, s28
	v_readfirstlane_b32 s28, v151
	global_load_lds_dwordx4 v[136:137], off
	v_lshl_add_u64 v[136:137], v[232:233], 0, s[94:95]
	s_mov_b32 m0, s28
	s_nop 0
	global_load_lds_dwordx4 v[136:137], off
	s_waitcnt vmcnt(8)
	s_waitcnt lgkmcnt(0)
	s_barrier
	s_setprio 1
	s_waitcnt lgkmcnt(0)
	v_mfma_f32_16x16x32_bf16 v[98:101], v[186:189], v[154:157], v[98:101]
	v_mfma_f32_16x16x32_bf16 v[66:69], v[186:189], v[162:165], v[66:69]
	v_mfma_f32_16x16x32_bf16 v[90:93], v[208:211], v[154:157], v[90:93]
	v_mfma_f32_16x16x32_bf16 v[58:61], v[208:211], v[162:165], v[58:61]
	v_mfma_f32_16x16x32_bf16 v[86:89], v[216:219], v[154:157], v[86:89]
	v_mfma_f32_16x16x32_bf16 v[42:45], v[216:219], v[162:165], v[42:45]
	v_mfma_f32_16x16x32_bf16 v[70:73], v[224:227], v[154:157], v[70:73]
	v_mfma_f32_16x16x32_bf16 v[28:31], v[224:227], v[162:165], v[28:31]
	v_mfma_f32_16x16x32_bf16 v[98:101], v[204:207], v[158:161], v[98:101]
	v_mfma_f32_16x16x32_bf16 v[66:69], v[204:207], v[166:169], v[66:69]
	v_mfma_f32_16x16x32_bf16 v[90:93], v[212:215], v[158:161], v[90:93]
	v_mfma_f32_16x16x32_bf16 v[58:61], v[212:215], v[166:169], v[58:61]
	v_mfma_f32_16x16x32_bf16 v[86:89], v[220:223], v[158:161], v[86:89]
	v_mfma_f32_16x16x32_bf16 v[42:45], v[220:223], v[166:169], v[42:45]
	v_mfma_f32_16x16x32_bf16 v[70:73], v[228:231], v[158:161], v[70:73]
	v_mfma_f32_16x16x32_bf16 v[28:31], v[228:231], v[166:169], v[28:31]
	s_setprio 0
	s_setprio 1
	v_mfma_f32_16x16x32_bf16 v[16:19], v[186:189], v[170:173], v[16:19]
	v_mfma_f32_16x16x32_bf16 v[4:7], v[186:189], v[178:181], v[4:7]
	v_mfma_f32_16x16x32_bf16 v[8:11], v[208:211], v[170:173], v[8:11]
	v_mfma_f32_16x16x32_bf16 v[0:3], v[208:211], v[178:181], v[0:3]
	v_mfma_f32_16x16x32_bf16 v[78:81], v[216:219], v[170:173], v[78:81]
	v_mfma_f32_16x16x32_bf16 v[46:49], v[216:219], v[178:181], v[46:49]
	v_mfma_f32_16x16x32_bf16 v[82:85], v[224:227], v[170:173], v[82:85]
	v_mfma_f32_16x16x32_bf16 v[50:53], v[224:227], v[178:181], v[50:53]
	v_mfma_f32_16x16x32_bf16 v[16:19], v[204:207], v[174:177], v[16:19]
	v_mfma_f32_16x16x32_bf16 v[4:7], v[204:207], v[182:185], v[4:7]
	v_mfma_f32_16x16x32_bf16 v[8:11], v[212:215], v[174:177], v[8:11]
	v_mfma_f32_16x16x32_bf16 v[0:3], v[212:215], v[182:185], v[0:3]
	v_mfma_f32_16x16x32_bf16 v[78:81], v[220:223], v[174:177], v[78:81]
	v_mfma_f32_16x16x32_bf16 v[46:49], v[220:223], v[182:185], v[46:49]
	v_mfma_f32_16x16x32_bf16 v[82:85], v[228:231], v[174:177], v[82:85]
	v_mfma_f32_16x16x32_bf16 v[50:53], v[228:231], v[182:185], v[50:53]
	s_setprio 0
	s_barrier
	s_add_i32 s87, s87, 2
	s_add_u32 s26, s26, 0x100
	s_addc_u32 s27, s27, 0
	s_cmp_gt_u32 s87, 13
	s_cbranch_scc0 .LBB0_374
	v_readlane_b32 s26, v254, 12
	v_readlane_b32 s27, v254, 13
	s_and_b64 vcc, exec, s[26:27]
	s_cbranch_vccz .LBB0_377
	s_barrier
